# heavy GEMM K-loops restructured: phase pairs merged (32 MFMA per barrier interval, 8 barriers/iter instead of 16), same DMA order, vmcnt(8)+lgkmcnt(0) before load-closing barriers
# speedup vs baseline: 1.0117x; 1.0117x over previous
.LBB0_661:
	s_and_b32 s0, 0xffff, s0
	s_cmp_eq_u32 s0, 56
	s_cselect_b32 s0, 2, 0
	s_and_b64 s[6:7], s[6:7], exec
	s_cselect_b32 s92, 1, s0
	s_lshl_b32 s0, s1, 5
	s_and_b32 s16, s0, 0x60
	s_mov_b64 s[0:1], 0x80
	s_add_i32 m0, s27, 0x18000
	v_lshl_add_u64 v[8:9], v[8:9], 0, s[0:1]
	s_ashr_i32 s79, s24, 31
	s_lshl_b32 s15, s14, 13
	s_lshl_b32 s17, s16, 7
	s_waitcnt vmcnt(0)
	s_barrier
	global_load_lds_dwordx4 v[8:9], off
	v_lshl_add_u64 v[6:7], v[6:7], 0, s[0:1]
	s_add_i32 m0, s27, 0x1a000
	s_add_i32 s80, s27, 0x8000
	s_add_i32 s81, s27, 0xa000
	global_load_lds_dwordx4 v[6:7], off
	v_lshl_add_u64 v[4:5], v[4:5], 0, s[0:1]
	s_mov_b32 m0, s80
	s_add_u32 s6, s34, 0x100080
	global_load_lds_dwordx4 v[4:5], off
	v_lshl_add_u64 v[2:3], v[2:3], 0, s[0:1]
	s_mov_b32 m0, s81
	s_addc_u32 s7, s35, 0
	global_load_lds_dwordx4 v[2:3], off
	s_add_i32 m0, s27, 0x1c000
	v_lshl_add_u64 v[2:3], s[6:7], 0, v[134:135]
	global_load_lds_dwordx4 v[2:3], off
	v_lshl_add_u64 v[2:3], s[6:7], 0, v[130:131]
	s_add_i32 m0, s27, 0x1e000
	s_add_u32 s83, s13, 0xfde00000
	global_load_lds_dwordx4 v[2:3], off
	v_lshrrev_b32_e32 v3, 1, v11
	v_and_b32_e32 v3, 24, v3
	v_and_b32_e32 v2, 15, v11
	v_lshlrev_b32_e32 v4, 1, v3
	v_lshl_or_b32 v1, s14, 6, v2
	v_lshl_or_b32 v2, v2, 6, v4
	v_lshlrev_b32_e32 v4, 2, v11
	v_and_b32_e32 v4, 32, v4
	v_or_b32_e32 v149, s16, v3
	v_bitop3_b32 v5, v2, s15, v4 bitop3:0xde
	v_bitop3_b32 v148, v2, s17, v4 bitop3:0xde
	v_lshlrev_b32_e32 v2, 2, v149
	v_mov_b32_e32 v3, v135
	v_lshl_add_u64 v[138:139], s[4:5], 0, v[2:3]
	v_lshlrev_b32_e32 v2, 16, v10
	v_and_b32_e32 v2, 0xfffe0000, v2
	v_lshl_add_u32 v2, v12, 13, v2
	v_and_b32_e32 v3, 1, v10
	v_lshl_or_b32 v2, v3, 6, v2
	v_lshl_add_u32 v140, v13, 1, v2
	v_lshlrev_b32_e32 v2, 16, v15
	v_and_b32_e32 v2, 0xfffe0000, v2
	s_waitcnt vmcnt(6)
	v_lshl_add_u32 v2, v14, 13, v2
	v_and_b32_e32 v3, 1, v15
	s_addc_u32 s84, s12, -1
	v_lshl_or_b32 v2, v3, 6, v2
	s_add_i32 s85, 0, 0x10000
	s_add_i32 s86, 0, 0x14000
	s_mov_b32 s82, 0
	v_mov_b32_e32 v141, v135
	v_lshl_add_u32 v142, v16, 1, v2
	v_mov_b32_e32 v143, v135
	v_mov_b64_e32 v[144:145], 0x791
	v_add_u32_e32 v150, s85, v148
	v_add_u32_e32 v151, 0, v5
	v_add_u32_e32 v152, s86, v148
	s_mov_b32 s87, 0x20000
	s_mov_b64 s[6:7], 0x24000
	s_mov_b32 s88, 0x24000
	s_mov_b64 s[12:13], 0x28000
	s_mov_b32 s89, 0x28000
	s_mov_b64 s[14:15], 0x2c000
	s_movk_i32 s90, 0x3900
	s_mov_b64 s[22:23], s[36:37]
	s_mov_b64 s[20:21], s[34:35]
	s_barrier
	s_branch .LBB0_663

.LBB0_670:
	ds_read_b128 v[154:157], v150
	ds_read_b128 v[158:161], v150 offset:1024
	ds_read_b128 v[162:165], v150 offset:2048
	ds_read_b128 v[166:169], v150 offset:3072
	ds_read_b128 v[202:205], v152
	ds_read_b128 v[206:209], v152 offset:1024
	ds_read_b128 v[210:213], v152 offset:2048
	ds_read_b128 v[214:217], v152 offset:3072
	s_add_u32 s28, s34, 0xfff00080
	s_addc_u32 s29, s35, -1
	s_cmp_eq_u32 s94, 60
	s_cselect_b32 s39, s23, s29
	s_cselect_b32 s38, s22, s28
	s_cselect_b32 s37, s21, s93
	s_cselect_b32 s36, s20, s19
	v_lshl_add_u64 v[146:147], s[34:35], 0, v[142:143]
	s_add_i32 m0, s27, 0xc000
	ds_read_b128 v[170:173], v151
	ds_read_b128 v[174:177], v151 offset:1024
	ds_read_b128 v[178:181], v151 offset:2048
	ds_read_b128 v[182:185], v151 offset:3072
	ds_read_b128 v[186:189], v151 offset:4096
	ds_read_b128 v[190:193], v151 offset:5120
	ds_read_b128 v[194:197], v151 offset:6144
	ds_read_b128 v[198:201], v151 offset:7168
	global_load_lds_dwordx4 v[146:147], off
	v_lshl_add_u64 v[146:147], s[34:35], 0, v[140:141]
	s_add_i32 m0, s27, 0xe000
	s_nop 0
	global_load_lds_dwordx4 v[146:147], off
	s_waitcnt vmcnt(8)
	s_waitcnt lgkmcnt(0)
	s_barrier
	s_setprio 1
	v_mfma_f32_16x16x32_bf16 v[126:129], v[154:157], v[170:173], v[126:129]
	v_mfma_f32_16x16x32_bf16 v[122:125], v[162:165], v[170:173], v[122:125]
	v_mfma_f32_16x16x32_bf16 v[118:121], v[154:157], v[178:181], v[118:121]
	v_mfma_f32_16x16x32_bf16 v[110:113], v[162:165], v[178:181], v[110:113]
	v_mfma_f32_16x16x32_bf16 v[102:105], v[154:157], v[186:189], v[102:105]
	v_mfma_f32_16x16x32_bf16 v[94:97], v[162:165], v[186:189], v[94:97]
	v_mfma_f32_16x16x32_bf16 v[86:89], v[154:157], v[194:197], v[86:89]
	v_mfma_f32_16x16x32_bf16 v[78:81], v[162:165], v[194:197], v[78:81]
	v_mfma_f32_16x16x32_bf16 v[126:129], v[158:161], v[174:177], v[126:129]
	v_mfma_f32_16x16x32_bf16 v[122:125], v[166:169], v[174:177], v[122:125]
	v_mfma_f32_16x16x32_bf16 v[118:121], v[158:161], v[182:185], v[118:121]
	v_mfma_f32_16x16x32_bf16 v[110:113], v[166:169], v[182:185], v[110:113]
	v_mfma_f32_16x16x32_bf16 v[102:105], v[158:161], v[190:193], v[102:105]
	v_mfma_f32_16x16x32_bf16 v[94:97], v[166:169], v[190:193], v[94:97]
	v_mfma_f32_16x16x32_bf16 v[86:89], v[158:161], v[198:201], v[86:89]
	v_mfma_f32_16x16x32_bf16 v[78:81], v[166:169], v[198:201], v[78:81]
	v_mfma_f32_16x16x32_bf16 v[114:117], v[202:205], v[170:173], v[114:117]
	v_mfma_f32_16x16x32_bf16 v[106:109], v[210:213], v[170:173], v[106:109]
	v_mfma_f32_16x16x32_bf16 v[98:101], v[202:205], v[178:181], v[98:101]
	v_mfma_f32_16x16x32_bf16 v[90:93], v[210:213], v[178:181], v[90:93]
	v_mfma_f32_16x16x32_bf16 v[82:85], v[202:205], v[186:189], v[82:85]
	v_mfma_f32_16x16x32_bf16 v[74:77], v[210:213], v[186:189], v[74:77]
	v_mfma_f32_16x16x32_bf16 v[70:73], v[202:205], v[194:197], v[70:73]
	v_mfma_f32_16x16x32_bf16 v[66:69], v[210:213], v[194:197], v[66:69]
	v_mfma_f32_16x16x32_bf16 v[114:117], v[206:209], v[174:177], v[114:117]
	v_mfma_f32_16x16x32_bf16 v[106:109], v[214:217], v[174:177], v[106:109]
	v_mfma_f32_16x16x32_bf16 v[98:101], v[206:209], v[182:185], v[98:101]
	v_mfma_f32_16x16x32_bf16 v[90:93], v[214:217], v[182:185], v[90:93]
	v_mfma_f32_16x16x32_bf16 v[82:85], v[206:209], v[190:193], v[82:85]
	v_mfma_f32_16x16x32_bf16 v[74:77], v[214:217], v[190:193], v[74:77]
	v_mfma_f32_16x16x32_bf16 v[70:73], v[206:209], v[198:201], v[70:73]
	v_mfma_f32_16x16x32_bf16 v[66:69], v[214:217], v[198:201], v[66:69]
	s_setprio 0
	s_barrier
	ds_read_b128 v[170:173], v151 offset:16384
	ds_read_b128 v[174:177], v151 offset:17408
	ds_read_b128 v[178:181], v151 offset:18432
	ds_read_b128 v[182:185], v151 offset:19456
	ds_read_b128 v[186:189], v151 offset:20480
	ds_read_b128 v[190:193], v151 offset:21504
	ds_read_b128 v[194:197], v151 offset:22528
	ds_read_b128 v[198:201], v151 offset:23552
	s_add_i32 s28, s85, s74
	v_lshl_add_u64 v[146:147], s[36:37], 0, v[134:135]
	s_mov_b32 m0, s28
	s_nop 0
	global_load_lds_dwordx4 v[146:147], off
	v_lshl_add_u64 v[218:219], s[36:37], 0, v[130:131]
	s_add_i32 m0, s28, 0x2000
	s_nop 0
	global_load_lds_dwordx4 v[218:219], off
	s_mov_b32 m0, s27
	v_lshl_add_u64 v[220:221], s[38:39], 0, v[136:137]
	global_load_lds_dwordx4 v[220:221], off
	v_lshl_add_u64 v[222:223], s[38:39], 0, v[132:133]
	s_mov_b32 m0, s76
	s_nop 0
	global_load_lds_dwordx4 v[222:223], off
	s_add_u32 s28, s36, 0x100000
	s_addc_u32 s29, s37, 0
	s_add_i32 s95, s86, s74
	v_lshl_add_u64 v[226:227], s[28:29], 0, v[134:135]
	s_mov_b32 m0, s95
	s_nop 0
	global_load_lds_dwordx4 v[226:227], off
	v_lshl_add_u64 v[226:227], s[28:29], 0, v[130:131]
	s_add_i32 m0, s95, 0x2000
	s_nop 0
	global_load_lds_dwordx4 v[226:227], off
	s_waitcnt vmcnt(8)
	s_waitcnt lgkmcnt(0)
	s_barrier
	s_setprio 1
	v_mfma_f32_16x16x32_bf16 v[62:65], v[154:157], v[170:173], v[62:65]
	v_mfma_f32_16x16x32_bf16 v[58:61], v[162:165], v[170:173], v[58:61]
	v_mfma_f32_16x16x32_bf16 v[54:57], v[154:157], v[178:181], v[54:57]
	v_mfma_f32_16x16x32_bf16 v[46:49], v[162:165], v[178:181], v[46:49]
	v_mfma_f32_16x16x32_bf16 v[38:41], v[154:157], v[186:189], v[38:41]
	v_mfma_f32_16x16x32_bf16 v[30:33], v[162:165], v[186:189], v[30:33]
	v_mfma_f32_16x16x32_bf16 v[22:25], v[154:157], v[194:197], v[22:25]
	v_mfma_f32_16x16x32_bf16 v[14:17], v[162:165], v[194:197], v[14:17]
	v_mfma_f32_16x16x32_bf16 v[62:65], v[158:161], v[174:177], v[62:65]
	v_mfma_f32_16x16x32_bf16 v[58:61], v[166:169], v[174:177], v[58:61]
	v_mfma_f32_16x16x32_bf16 v[54:57], v[158:161], v[182:185], v[54:57]
	v_mfma_f32_16x16x32_bf16 v[46:49], v[166:169], v[182:185], v[46:49]
	v_mfma_f32_16x16x32_bf16 v[38:41], v[158:161], v[190:193], v[38:41]
	v_mfma_f32_16x16x32_bf16 v[30:33], v[166:169], v[190:193], v[30:33]
	v_mfma_f32_16x16x32_bf16 v[22:25], v[158:161], v[198:201], v[22:25]
	v_mfma_f32_16x16x32_bf16 v[14:17], v[166:169], v[198:201], v[14:17]
	v_mfma_f32_16x16x32_bf16 v[50:53], v[202:205], v[170:173], v[50:53]
	v_mfma_f32_16x16x32_bf16 v[42:45], v[210:213], v[170:173], v[42:45]
	v_mfma_f32_16x16x32_bf16 v[34:37], v[202:205], v[178:181], v[34:37]
	v_mfma_f32_16x16x32_bf16 v[26:29], v[210:213], v[178:181], v[26:29]
	v_mfma_f32_16x16x32_bf16 v[18:21], v[202:205], v[186:189], v[18:21]
	v_mfma_f32_16x16x32_bf16 v[10:13], v[210:213], v[186:189], v[10:13]
	v_mfma_f32_16x16x32_bf16 v[6:9], v[202:205], v[194:197], v[6:9]
	v_mfma_f32_16x16x32_bf16 v[2:5], v[210:213], v[194:197], v[2:5]
	v_mfma_f32_16x16x32_bf16 v[50:53], v[206:209], v[174:177], v[50:53]
	v_mfma_f32_16x16x32_bf16 v[42:45], v[214:217], v[174:177], v[42:45]
	v_mfma_f32_16x16x32_bf16 v[34:37], v[206:209], v[182:185], v[34:37]
	v_mfma_f32_16x16x32_bf16 v[26:29], v[214:217], v[182:185], v[26:29]
	v_mfma_f32_16x16x32_bf16 v[18:21], v[206:209], v[190:193], v[18:21]
	v_mfma_f32_16x16x32_bf16 v[10:13], v[214:217], v[190:193], v[10:13]
	v_mfma_f32_16x16x32_bf16 v[6:9], v[206:209], v[198:201], v[6:9]
	v_mfma_f32_16x16x32_bf16 v[2:5], v[214:217], v[198:201], v[2:5]
	s_setprio 0
	s_add_i32 s95, 0, 0x18000
	v_add_u32_e32 v153, s95, v148
	s_barrier
	ds_read_b128 v[154:157], v153
	ds_read_b128 v[158:161], v153 offset:1024
	ds_read_b128 v[162:165], v153 offset:2048
	ds_read_b128 v[166:169], v153 offset:3072
	ds_read_b128 v[202:205], v153 offset:16384
	ds_read_b128 v[206:209], v153 offset:17408
	ds_read_b128 v[210:213], v153 offset:18432
	ds_read_b128 v[214:217], v153 offset:19456
	s_add_u32 s28, s38, 0x100000
	s_addc_u32 s29, s39, 0
	s_mov_b32 m0, s77
	v_lshl_add_u64 v[226:227], s[28:29], 0, v[136:137]
	ds_read_b128 v[170:173], v151 offset:32768
	ds_read_b128 v[174:177], v151 offset:33792
	ds_read_b128 v[178:181], v151 offset:34816
	ds_read_b128 v[182:185], v151 offset:35840
	ds_read_b128 v[186:189], v151 offset:36864
	ds_read_b128 v[190:193], v151 offset:37888
	ds_read_b128 v[194:197], v151 offset:38912
	ds_read_b128 v[198:201], v151 offset:39936
	global_load_lds_dwordx4 v[226:227], off
	v_lshl_add_u64 v[226:227], s[28:29], 0, v[132:133]
	s_mov_b32 m0, s78
	s_nop 0
	global_load_lds_dwordx4 v[226:227], off
	s_waitcnt vmcnt(8)
	s_waitcnt lgkmcnt(0)
	s_barrier
	s_setprio 1
	v_mfma_f32_16x16x32_bf16 v[126:129], v[154:157], v[170:173], v[126:129]
	v_mfma_f32_16x16x32_bf16 v[122:125], v[162:165], v[170:173], v[122:125]
	v_mfma_f32_16x16x32_bf16 v[118:121], v[154:157], v[178:181], v[118:121]
	v_mfma_f32_16x16x32_bf16 v[110:113], v[162:165], v[178:181], v[110:113]
	v_mfma_f32_16x16x32_bf16 v[102:105], v[154:157], v[186:189], v[102:105]
	v_mfma_f32_16x16x32_bf16 v[94:97], v[162:165], v[186:189], v[94:97]
	v_mfma_f32_16x16x32_bf16 v[86:89], v[154:157], v[194:197], v[86:89]
	v_mfma_f32_16x16x32_bf16 v[78:81], v[162:165], v[194:197], v[78:81]
	v_mfma_f32_16x16x32_bf16 v[126:129], v[158:161], v[174:177], v[126:129]
	v_mfma_f32_16x16x32_bf16 v[122:125], v[166:169], v[174:177], v[122:125]
	v_mfma_f32_16x16x32_bf16 v[118:121], v[158:161], v[182:185], v[118:121]
	v_mfma_f32_16x16x32_bf16 v[110:113], v[166:169], v[182:185], v[110:113]
	v_mfma_f32_16x16x32_bf16 v[102:105], v[158:161], v[190:193], v[102:105]
	v_mfma_f32_16x16x32_bf16 v[94:97], v[166:169], v[190:193], v[94:97]
	v_mfma_f32_16x16x32_bf16 v[86:89], v[158:161], v[198:201], v[86:89]
	v_mfma_f32_16x16x32_bf16 v[78:81], v[166:169], v[198:201], v[78:81]
	v_mfma_f32_16x16x32_bf16 v[114:117], v[202:205], v[170:173], v[114:117]
	v_mfma_f32_16x16x32_bf16 v[106:109], v[210:213], v[170:173], v[106:109]
	v_mfma_f32_16x16x32_bf16 v[98:101], v[202:205], v[178:181], v[98:101]
	v_mfma_f32_16x16x32_bf16 v[90:93], v[210:213], v[178:181], v[90:93]
	v_mfma_f32_16x16x32_bf16 v[82:85], v[202:205], v[186:189], v[82:85]
	v_mfma_f32_16x16x32_bf16 v[74:77], v[210:213], v[186:189], v[74:77]
	v_mfma_f32_16x16x32_bf16 v[70:73], v[202:205], v[194:197], v[70:73]
	v_mfma_f32_16x16x32_bf16 v[66:69], v[210:213], v[194:197], v[66:69]
	v_mfma_f32_16x16x32_bf16 v[114:117], v[206:209], v[174:177], v[114:117]
	v_mfma_f32_16x16x32_bf16 v[106:109], v[214:217], v[174:177], v[106:109]
	v_mfma_f32_16x16x32_bf16 v[98:101], v[206:209], v[182:185], v[98:101]
	v_mfma_f32_16x16x32_bf16 v[90:93], v[214:217], v[182:185], v[90:93]
	v_mfma_f32_16x16x32_bf16 v[82:85], v[206:209], v[190:193], v[82:85]
	v_mfma_f32_16x16x32_bf16 v[74:77], v[214:217], v[190:193], v[74:77]
	v_mfma_f32_16x16x32_bf16 v[70:73], v[206:209], v[198:201], v[70:73]
	v_mfma_f32_16x16x32_bf16 v[66:69], v[214:217], v[198:201], v[66:69]
	s_setprio 0
	s_barrier
	ds_read_b128 v[170:173], v151 offset:49152
	ds_read_b128 v[174:177], v151 offset:50176
	ds_read_b128 v[178:181], v151 offset:51200
	ds_read_b128 v[182:185], v151 offset:52224
	ds_read_b128 v[186:189], v151 offset:53248
	ds_read_b128 v[190:193], v151 offset:54272
	ds_read_b128 v[194:197], v151 offset:55296
	ds_read_b128 v[198:201], v151 offset:56320
	s_add_i32 s38, 0, 0x1c000
	s_add_i32 s28, s95, s74
	v_lshl_add_u64 v[146:147], v[146:147], 0, s[0:1]
	s_mov_b32 m0, s28
	s_nop 0
	global_load_lds_dwordx4 v[146:147], off
	v_lshl_add_u64 v[146:147], v[218:219], 0, s[0:1]
	s_add_i32 m0, s28, 0x2000
	s_nop 0
	global_load_lds_dwordx4 v[146:147], off
	s_mov_b32 m0, s80
	v_lshl_add_u64 v[146:147], v[220:221], 0, s[0:1]
	global_load_lds_dwordx4 v[146:147], off
	v_lshl_add_u64 v[146:147], v[222:223], 0, s[0:1]
	s_mov_b32 m0, s81
	s_nop 0
	global_load_lds_dwordx4 v[146:147], off
	s_add_u32 s28, s36, 0x100080
	s_addc_u32 s29, s37, 0
	s_add_i32 s36, s38, s74
	v_lshl_add_u64 v[146:147], s[28:29], 0, v[134:135]
	s_mov_b32 m0, s36
	s_nop 0
	global_load_lds_dwordx4 v[146:147], off
	v_lshl_add_u64 v[146:147], s[28:29], 0, v[130:131]
	s_add_i32 m0, s36, 0x2000
	s_nop 0
	global_load_lds_dwordx4 v[146:147], off
	s_waitcnt vmcnt(8)
	s_waitcnt lgkmcnt(0)
	s_barrier
	s_setprio 1
	v_mfma_f32_16x16x32_bf16 v[62:65], v[154:157], v[170:173], v[62:65]
	v_mfma_f32_16x16x32_bf16 v[58:61], v[162:165], v[170:173], v[58:61]
	v_mfma_f32_16x16x32_bf16 v[54:57], v[154:157], v[178:181], v[54:57]
	v_mfma_f32_16x16x32_bf16 v[46:49], v[162:165], v[178:181], v[46:49]
	v_mfma_f32_16x16x32_bf16 v[38:41], v[154:157], v[186:189], v[38:41]
	v_mfma_f32_16x16x32_bf16 v[30:33], v[162:165], v[186:189], v[30:33]
	v_mfma_f32_16x16x32_bf16 v[22:25], v[154:157], v[194:197], v[22:25]
	v_mfma_f32_16x16x32_bf16 v[14:17], v[162:165], v[194:197], v[14:17]
	v_mfma_f32_16x16x32_bf16 v[62:65], v[158:161], v[174:177], v[62:65]
	v_mfma_f32_16x16x32_bf16 v[58:61], v[166:169], v[174:177], v[58:61]
	v_mfma_f32_16x16x32_bf16 v[54:57], v[158:161], v[182:185], v[54:57]
	v_mfma_f32_16x16x32_bf16 v[46:49], v[166:169], v[182:185], v[46:49]
	v_mfma_f32_16x16x32_bf16 v[38:41], v[158:161], v[190:193], v[38:41]
	v_mfma_f32_16x16x32_bf16 v[30:33], v[166:169], v[190:193], v[30:33]
	v_mfma_f32_16x16x32_bf16 v[22:25], v[158:161], v[198:201], v[22:25]
	v_mfma_f32_16x16x32_bf16 v[14:17], v[166:169], v[198:201], v[14:17]
	v_mfma_f32_16x16x32_bf16 v[50:53], v[202:205], v[170:173], v[50:53]
	v_mfma_f32_16x16x32_bf16 v[42:45], v[210:213], v[170:173], v[42:45]
	v_mfma_f32_16x16x32_bf16 v[34:37], v[202:205], v[178:181], v[34:37]
	v_mfma_f32_16x16x32_bf16 v[26:29], v[210:213], v[178:181], v[26:29]
	v_mfma_f32_16x16x32_bf16 v[18:21], v[202:205], v[186:189], v[18:21]
	v_mfma_f32_16x16x32_bf16 v[10:13], v[210:213], v[186:189], v[10:13]
	v_mfma_f32_16x16x32_bf16 v[6:9], v[202:205], v[194:197], v[6:9]
	v_mfma_f32_16x16x32_bf16 v[2:5], v[210:213], v[194:197], v[2:5]
	v_mfma_f32_16x16x32_bf16 v[50:53], v[206:209], v[174:177], v[50:53]
	v_mfma_f32_16x16x32_bf16 v[42:45], v[214:217], v[174:177], v[42:45]
	v_mfma_f32_16x16x32_bf16 v[34:37], v[206:209], v[182:185], v[34:37]
	v_mfma_f32_16x16x32_bf16 v[26:29], v[214:217], v[182:185], v[26:29]
	v_mfma_f32_16x16x32_bf16 v[18:21], v[206:209], v[190:193], v[18:21]
	v_mfma_f32_16x16x32_bf16 v[10:13], v[214:217], v[190:193], v[10:13]
	v_mfma_f32_16x16x32_bf16 v[6:9], v[206:209], v[198:201], v[6:9]
	v_mfma_f32_16x16x32_bf16 v[2:5], v[214:217], v[198:201], v[2:5]
	s_setprio 0
	s_add_i32 s94, s94, 2
	s_add_u32 s19, s19, 0x100
	s_addc_u32 s93, s93, 0
	s_add_u32 s34, s34, 0x100
	s_addc_u32 s35, s35, 0
	s_cmp_gt_u32 s94, 61
	s_barrier
	s_cbranch_scc0 .LBB0_670
	s_cmp_lt_i32 s92, 2
	s_cbranch_scc1 .LBB0_675
	s_cmp_eq_u32 s92, 2
	s_mov_b64 s[34:35], -1
	s_cbranch_scc0 .LBB0_674
	v_lshl_add_u32 v146, s26, 8, v1
	v_or_b32_e32 v156, 16, v146
	v_ashrrev_i32_e32 v147, 31, v146
	v_ashrrev_i32_e32 v157, 31, v156
	v_lshlrev_b64 v[154:155], 10, v[146:147]
	v_lshlrev_b64 v[156:157], 10, v[156:157]
	v_lshl_add_u64 v[154:155], v[138:139], 0, v[154:155]
	v_lshl_add_u64 v[156:157], v[138:139], 0, v[156:157]
	global_store_dwordx4 v[154:155], v[126:129], off
	global_store_dwordx4 v[154:155], v[122:125], off offset:16
	global_store_dwordx4 v[154:155], v[114:117], off offset:512
	global_store_dwordx4 v[154:155], v[106:109], off offset:528
	global_store_dwordx4 v[156:157], v[118:121], off
	global_store_dwordx4 v[156:157], v[110:113], off offset:16
	global_store_dwordx4 v[156:157], v[98:101], off offset:512
	global_store_dwordx4 v[156:157], v[90:93], off offset:528
	v_or_b32_e32 v156, 32, v146
	v_ashrrev_i32_e32 v157, 31, v156
	v_lshlrev_b64 v[156:157], 10, v[156:157]
	v_or_b32_e32 v146, 48, v146
	v_lshl_add_u64 v[156:157], v[138:139], 0, v[156:157]
	v_ashrrev_i32_e32 v147, 31, v146
	global_store_dwordx4 v[156:157], v[102:105], off
	global_store_dwordx4 v[156:157], v[94:97], off offset:16
	global_store_dwordx4 v[156:157], v[82:85], off offset:512
	global_store_dwordx4 v[156:157], v[74:77], off offset:528
	v_lshlrev_b64 v[146:147], 10, v[146:147]
	v_add_co_u32_e32 v156, vcc, s87, v154
	v_lshl_add_u64 v[146:147], v[138:139], 0, v[146:147]
	s_mov_b64 s[28:29], 0x20000
	v_addc_co_u32_e32 v157, vcc, 0, v155, vcc
	global_store_dwordx4 v[146:147], v[86:89], off
	global_store_dwordx4 v[146:147], v[78:81], off offset:16
	global_store_dwordx4 v[146:147], v[70:73], off offset:512
	global_store_dwordx4 v[146:147], v[66:69], off offset:528
	v_lshl_add_u64 v[146:147], v[154:155], 0, s[28:29]
	global_store_dwordx4 v[156:157], v[62:65], off
	global_store_dwordx4 v[146:147], v[58:61], off offset:16
	global_store_dwordx4 v[146:147], v[50:53], off offset:512
	global_store_dwordx4 v[146:147], v[42:45], off offset:528
	v_add_co_u32_e32 v156, vcc, s88, v154
	v_lshl_add_u64 v[146:147], v[154:155], 0, s[6:7]
	s_nop 0
	v_addc_co_u32_e32 v157, vcc, 0, v155, vcc
	global_store_dwordx4 v[156:157], v[54:57], off
	global_store_dwordx4 v[146:147], v[46:49], off offset:16
	global_store_dwordx4 v[146:147], v[34:37], off offset:512
	global_store_dwordx4 v[146:147], v[26:29], off offset:528
	v_add_co_u32_e32 v156, vcc, s89, v154
	v_lshl_add_u64 v[146:147], v[154:155], 0, s[12:13]
	s_nop 0
	v_addc_co_u32_e32 v157, vcc, 0, v155, vcc
	global_store_dwordx4 v[156:157], v[38:41], off
	global_store_dwordx4 v[146:147], v[30:33], off offset:16
	global_store_dwordx4 v[146:147], v[18:21], off offset:512
	global_store_dwordx4 v[146:147], v[10:13], off offset:528
	v_lshl_add_u64 v[146:147], v[154:155], 0, s[14:15]
	v_add_co_u32_e32 v154, vcc, 0x2c000, v154
	s_mov_b64 s[34:35], 0
	s_nop 0
	v_addc_co_u32_e32 v155, vcc, 0, v155, vcc
	global_store_dwordx4 v[154:155], v[22:25], off
	global_store_dwordx4 v[146:147], v[14:17], off offset:16
	global_store_dwordx4 v[146:147], v[6:9], off offset:512
	global_store_dwordx4 v[146:147], v[2:5], off offset:528

.LBB0_2477:
	s_lshl_b32 s22, s22, 5
	s_and_b32 s29, s22, 0x60
	s_mov_b64 s[22:23], 0x80
	s_add_i32 m0, s49, 0x18000
	v_lshl_add_u64 v[8:9], v[8:9], 0, s[22:23]
	s_lshl_b32 s28, s7, 13
	s_lshl_b32 s34, s29, 7
	s_waitcnt vmcnt(0)
	s_barrier
	global_load_lds_dwordx4 v[8:9], off
	v_lshl_add_u64 v[6:7], v[6:7], 0, s[22:23]
	s_add_i32 m0, s49, 0x1a000
	s_add_i32 s72, s49, 0x8000
	s_add_i32 s73, s49, 0xa000
	global_load_lds_dwordx4 v[6:7], off
	v_lshl_add_u64 v[4:5], v[4:5], 0, s[22:23]
	s_mov_b32 m0, s72
	s_add_u32 s26, s52, 0x100080
	global_load_lds_dwordx4 v[4:5], off
	v_lshl_add_u64 v[2:3], v[2:3], 0, s[22:23]
	s_mov_b32 m0, s73
	s_addc_u32 s27, s53, 0
	global_load_lds_dwordx4 v[2:3], off
	s_add_i32 m0, s49, 0x1c000
	v_lshl_add_u64 v[2:3], s[26:27], 0, v[134:135]
	global_load_lds_dwordx4 v[2:3], off
	v_lshl_add_u64 v[2:3], s[26:27], 0, v[130:131]
	s_add_i32 m0, s49, 0x1e000
	s_add_i32 s74, 0, 0x10000
	global_load_lds_dwordx4 v[2:3], off
	v_lshrrev_b32_e32 v3, 1, v10
	v_and_b32_e32 v3, 24, v3
	v_and_b32_e32 v2, 15, v10
	v_lshlrev_b32_e32 v4, 1, v3
	v_lshl_or_b32 v1, s7, 6, v2
	v_lshl_or_b32 v2, v2, 6, v4
	v_lshlrev_b32_e32 v4, 2, v10
	v_and_b32_e32 v4, 32, v4
	v_bitop3_b32 v5, v2, s28, v4 bitop3:0xde
	v_bitop3_b32 v146, v2, s34, v4 bitop3:0xde
	v_lshlrev_b32_e32 v2, 16, v11
	v_and_b32_e32 v2, 0xfffe0000, v2
	v_or_b32_e32 v147, s29, v3
	v_lshl_add_u32 v2, v12, 13, v2
	v_and_b32_e32 v3, 1, v11
	v_lshl_or_b32 v2, v3, 6, v2
	v_lshl_add_u32 v138, v13, 1, v2
	v_lshlrev_b32_e32 v2, 16, v15
	v_and_b32_e32 v2, 0xfffe0000, v2
	s_waitcnt vmcnt(6)
	v_lshl_add_u32 v2, v14, 13, v2
	v_and_b32_e32 v3, 1, v15
	v_lshl_or_b32 v2, v3, 6, v2
	s_add_i32 s75, 0, 0x14000
	s_sext_i32_i8 s80, s6
	v_mov_b32_e32 v139, v135
	v_lshl_add_u32 v140, v16, 1, v2
	v_mov_b32_e32 v141, v135
	v_mov_b64_e32 v[142:143], 0x1ff
	v_add_u32_e32 v148, s74, v146
	v_add_u32_e32 v149, 0, v5
	v_add_u32_e32 v150, s75, v146
	s_mov_b32 s76, 0x100000
	s_mov_b64 s[26:27], 0x120000
	s_mov_b32 s77, 0x120000
	s_mov_b64 s[34:35], 0x140000
	s_mov_b32 s78, 0x140000
	s_mov_b64 s[36:37], 0x160000
	s_mov_b32 s79, 0x160000
	s_mov_b64 s[44:45], s[50:51]
	s_mov_b64 s[46:47], s[52:53]
	s_barrier

.LBB0_2485:
	ds_read_b128 v[152:155], v148
	ds_read_b128 v[156:159], v148 offset:1024
	ds_read_b128 v[160:163], v148 offset:2048
	ds_read_b128 v[164:167], v148 offset:3072
	ds_read_b128 v[200:203], v150
	ds_read_b128 v[204:207], v150 offset:1024
	ds_read_b128 v[208:211], v150 offset:2048
	ds_read_b128 v[212:215], v150 offset:3072
	s_add_u32 s28, s50, 0xfff00080
	s_addc_u32 s29, s51, -1
	s_cmp_eq_u32 s81, 60
	s_cselect_b32 s55, s45, s29
	s_cselect_b32 s54, s44, s28
	s_cselect_b32 s53, s47, s41
	s_cselect_b32 s52, s46, s39
	v_lshl_add_u64 v[144:145], s[50:51], 0, v[140:141]
	s_add_i32 m0, s49, 0xc000
	ds_read_b128 v[168:171], v149
	ds_read_b128 v[172:175], v149 offset:1024
	ds_read_b128 v[176:179], v149 offset:2048
	ds_read_b128 v[180:183], v149 offset:3072
	ds_read_b128 v[184:187], v149 offset:4096
	ds_read_b128 v[188:191], v149 offset:5120
	ds_read_b128 v[192:195], v149 offset:6144
	ds_read_b128 v[196:199], v149 offset:7168
	global_load_lds_dwordx4 v[144:145], off
	v_lshl_add_u64 v[144:145], s[50:51], 0, v[138:139]
	s_add_i32 m0, s49, 0xe000
	s_nop 0
	global_load_lds_dwordx4 v[144:145], off
	s_waitcnt vmcnt(8)
	s_waitcnt lgkmcnt(0)
	s_barrier
	s_setprio 1
	v_mfma_f32_16x16x32_bf16 v[126:129], v[152:155], v[168:171], v[126:129]
	v_mfma_f32_16x16x32_bf16 v[122:125], v[160:163], v[168:171], v[122:125]
	v_mfma_f32_16x16x32_bf16 v[114:117], v[152:155], v[176:179], v[114:117]
	v_mfma_f32_16x16x32_bf16 v[106:109], v[160:163], v[176:179], v[106:109]
	v_mfma_f32_16x16x32_bf16 v[98:101], v[152:155], v[184:187], v[98:101]
	v_mfma_f32_16x16x32_bf16 v[90:93], v[160:163], v[184:187], v[90:93]
	v_mfma_f32_16x16x32_bf16 v[82:85], v[152:155], v[192:195], v[82:85]
	v_mfma_f32_16x16x32_bf16 v[74:77], v[160:163], v[192:195], v[74:77]
	v_mfma_f32_16x16x32_bf16 v[126:129], v[156:159], v[172:175], v[126:129]
	v_mfma_f32_16x16x32_bf16 v[122:125], v[164:167], v[172:175], v[122:125]
	v_mfma_f32_16x16x32_bf16 v[114:117], v[156:159], v[180:183], v[114:117]
	v_mfma_f32_16x16x32_bf16 v[106:109], v[164:167], v[180:183], v[106:109]
	v_mfma_f32_16x16x32_bf16 v[98:101], v[156:159], v[188:191], v[98:101]
	v_mfma_f32_16x16x32_bf16 v[90:93], v[164:167], v[188:191], v[90:93]
	v_mfma_f32_16x16x32_bf16 v[82:85], v[156:159], v[196:199], v[82:85]
	v_mfma_f32_16x16x32_bf16 v[74:77], v[164:167], v[196:199], v[74:77]
	v_mfma_f32_16x16x32_bf16 v[118:121], v[200:203], v[168:171], v[118:121]
	v_mfma_f32_16x16x32_bf16 v[110:113], v[208:211], v[168:171], v[110:113]
	v_mfma_f32_16x16x32_bf16 v[102:105], v[200:203], v[176:179], v[102:105]
	v_mfma_f32_16x16x32_bf16 v[94:97], v[208:211], v[176:179], v[94:97]
	v_mfma_f32_16x16x32_bf16 v[86:89], v[200:203], v[184:187], v[86:89]
	v_mfma_f32_16x16x32_bf16 v[78:81], v[208:211], v[184:187], v[78:81]
	v_mfma_f32_16x16x32_bf16 v[70:73], v[200:203], v[192:195], v[70:73]
	v_mfma_f32_16x16x32_bf16 v[66:69], v[208:211], v[192:195], v[66:69]
	v_mfma_f32_16x16x32_bf16 v[118:121], v[204:207], v[172:175], v[118:121]
	v_mfma_f32_16x16x32_bf16 v[110:113], v[212:215], v[172:175], v[110:113]
	v_mfma_f32_16x16x32_bf16 v[102:105], v[204:207], v[180:183], v[102:105]
	v_mfma_f32_16x16x32_bf16 v[94:97], v[212:215], v[180:183], v[94:97]
	v_mfma_f32_16x16x32_bf16 v[86:89], v[204:207], v[188:191], v[86:89]
	v_mfma_f32_16x16x32_bf16 v[78:81], v[212:215], v[188:191], v[78:81]
	v_mfma_f32_16x16x32_bf16 v[70:73], v[204:207], v[196:199], v[70:73]
	v_mfma_f32_16x16x32_bf16 v[66:69], v[212:215], v[196:199], v[66:69]
	s_setprio 0
	s_barrier
	ds_read_b128 v[168:171], v149 offset:16384
	ds_read_b128 v[172:175], v149 offset:17408
	ds_read_b128 v[176:179], v149 offset:18432
	ds_read_b128 v[180:183], v149 offset:19456
	ds_read_b128 v[184:187], v149 offset:20480
	ds_read_b128 v[188:191], v149 offset:21504
	ds_read_b128 v[192:195], v149 offset:22528
	ds_read_b128 v[196:199], v149 offset:23552
	s_add_i32 s28, s74, s67
	v_lshl_add_u64 v[144:145], s[52:53], 0, v[134:135]
	s_mov_b32 m0, s28
	s_nop 0
	global_load_lds_dwordx4 v[144:145], off
	v_lshl_add_u64 v[216:217], s[52:53], 0, v[130:131]
	s_add_i32 m0, s28, 0x2000
	s_nop 0
	global_load_lds_dwordx4 v[216:217], off
	s_mov_b32 m0, s49
	v_lshl_add_u64 v[218:219], s[54:55], 0, v[136:137]
	global_load_lds_dwordx4 v[218:219], off
	v_lshl_add_u64 v[220:221], s[54:55], 0, v[132:133]
	s_mov_b32 m0, s68
	s_nop 0
	global_load_lds_dwordx4 v[220:221], off
	s_add_u32 s28, s52, 0x100000
	s_addc_u32 s29, s53, 0
	s_add_i32 s82, s75, s67
	v_lshl_add_u64 v[226:227], s[28:29], 0, v[134:135]
	s_mov_b32 m0, s82
	s_nop 0
	global_load_lds_dwordx4 v[226:227], off
	v_lshl_add_u64 v[226:227], s[28:29], 0, v[130:131]
	s_add_i32 m0, s82, 0x2000
	s_nop 0
	global_load_lds_dwordx4 v[226:227], off
	s_waitcnt vmcnt(8)
	s_waitcnt lgkmcnt(0)
	s_barrier
	s_setprio 1
	v_mfma_f32_16x16x32_bf16 v[62:65], v[152:155], v[168:171], v[62:65]
	v_mfma_f32_16x16x32_bf16 v[58:61], v[160:163], v[168:171], v[58:61]
	v_mfma_f32_16x16x32_bf16 v[54:57], v[152:155], v[176:179], v[54:57]
	v_mfma_f32_16x16x32_bf16 v[46:49], v[160:163], v[176:179], v[46:49]
	v_mfma_f32_16x16x32_bf16 v[38:41], v[152:155], v[184:187], v[38:41]
	v_mfma_f32_16x16x32_bf16 v[30:33], v[160:163], v[184:187], v[30:33]
	v_mfma_f32_16x16x32_bf16 v[22:25], v[152:155], v[192:195], v[22:25]
	v_mfma_f32_16x16x32_bf16 v[14:17], v[160:163], v[192:195], v[14:17]
	v_mfma_f32_16x16x32_bf16 v[62:65], v[156:159], v[172:175], v[62:65]
	v_mfma_f32_16x16x32_bf16 v[58:61], v[164:167], v[172:175], v[58:61]
	v_mfma_f32_16x16x32_bf16 v[54:57], v[156:159], v[180:183], v[54:57]
	v_mfma_f32_16x16x32_bf16 v[46:49], v[164:167], v[180:183], v[46:49]
	v_mfma_f32_16x16x32_bf16 v[38:41], v[156:159], v[188:191], v[38:41]
	v_mfma_f32_16x16x32_bf16 v[30:33], v[164:167], v[188:191], v[30:33]
	v_mfma_f32_16x16x32_bf16 v[22:25], v[156:159], v[196:199], v[22:25]
	v_mfma_f32_16x16x32_bf16 v[14:17], v[164:167], v[196:199], v[14:17]
	v_mfma_f32_16x16x32_bf16 v[50:53], v[200:203], v[168:171], v[50:53]
	v_mfma_f32_16x16x32_bf16 v[42:45], v[208:211], v[168:171], v[42:45]
	v_mfma_f32_16x16x32_bf16 v[34:37], v[200:203], v[176:179], v[34:37]
	v_mfma_f32_16x16x32_bf16 v[26:29], v[208:211], v[176:179], v[26:29]
	v_mfma_f32_16x16x32_bf16 v[18:21], v[200:203], v[184:187], v[18:21]
	v_mfma_f32_16x16x32_bf16 v[10:13], v[208:211], v[184:187], v[10:13]
	v_mfma_f32_16x16x32_bf16 v[6:9], v[200:203], v[192:195], v[6:9]
	v_mfma_f32_16x16x32_bf16 v[2:5], v[208:211], v[192:195], v[2:5]
	v_mfma_f32_16x16x32_bf16 v[50:53], v[204:207], v[172:175], v[50:53]
	v_mfma_f32_16x16x32_bf16 v[42:45], v[212:215], v[172:175], v[42:45]
	v_mfma_f32_16x16x32_bf16 v[34:37], v[204:207], v[180:183], v[34:37]
	v_mfma_f32_16x16x32_bf16 v[26:29], v[212:215], v[180:183], v[26:29]
	v_mfma_f32_16x16x32_bf16 v[18:21], v[204:207], v[188:191], v[18:21]
	v_mfma_f32_16x16x32_bf16 v[10:13], v[212:215], v[188:191], v[10:13]
	v_mfma_f32_16x16x32_bf16 v[6:9], v[204:207], v[196:199], v[6:9]
	v_mfma_f32_16x16x32_bf16 v[2:5], v[212:215], v[196:199], v[2:5]
	s_setprio 0
	s_add_i32 s82, 0, 0x18000
	v_add_u32_e32 v151, s82, v146
	s_barrier
	ds_read_b128 v[152:155], v151
	ds_read_b128 v[156:159], v151 offset:1024
	ds_read_b128 v[160:163], v151 offset:2048
	ds_read_b128 v[164:167], v151 offset:3072
	ds_read_b128 v[200:203], v151 offset:16384
	ds_read_b128 v[204:207], v151 offset:17408
	ds_read_b128 v[208:211], v151 offset:18432
	ds_read_b128 v[212:215], v151 offset:19456
	s_add_u32 s28, s54, 0x100000
	s_addc_u32 s29, s55, 0
	s_mov_b32 m0, s69
	v_lshl_add_u64 v[226:227], s[28:29], 0, v[136:137]
	ds_read_b128 v[168:171], v149 offset:32768
	ds_read_b128 v[172:175], v149 offset:33792
	ds_read_b128 v[176:179], v149 offset:34816
	ds_read_b128 v[180:183], v149 offset:35840
	ds_read_b128 v[184:187], v149 offset:36864
	ds_read_b128 v[188:191], v149 offset:37888
	ds_read_b128 v[192:195], v149 offset:38912
	ds_read_b128 v[196:199], v149 offset:39936
	global_load_lds_dwordx4 v[226:227], off
	v_lshl_add_u64 v[226:227], s[28:29], 0, v[132:133]
	s_mov_b32 m0, s70
	s_nop 0
	global_load_lds_dwordx4 v[226:227], off
	s_waitcnt vmcnt(8)
	s_waitcnt lgkmcnt(0)
	s_barrier
	s_setprio 1
	v_mfma_f32_16x16x32_bf16 v[126:129], v[152:155], v[168:171], v[126:129]
	v_mfma_f32_16x16x32_bf16 v[122:125], v[160:163], v[168:171], v[122:125]
	v_mfma_f32_16x16x32_bf16 v[114:117], v[152:155], v[176:179], v[114:117]
	v_mfma_f32_16x16x32_bf16 v[106:109], v[160:163], v[176:179], v[106:109]
	v_mfma_f32_16x16x32_bf16 v[98:101], v[152:155], v[184:187], v[98:101]
	v_mfma_f32_16x16x32_bf16 v[90:93], v[160:163], v[184:187], v[90:93]
	v_mfma_f32_16x16x32_bf16 v[82:85], v[152:155], v[192:195], v[82:85]
	v_mfma_f32_16x16x32_bf16 v[74:77], v[160:163], v[192:195], v[74:77]
	v_mfma_f32_16x16x32_bf16 v[126:129], v[156:159], v[172:175], v[126:129]
	v_mfma_f32_16x16x32_bf16 v[122:125], v[164:167], v[172:175], v[122:125]
	v_mfma_f32_16x16x32_bf16 v[114:117], v[156:159], v[180:183], v[114:117]
	v_mfma_f32_16x16x32_bf16 v[106:109], v[164:167], v[180:183], v[106:109]
	v_mfma_f32_16x16x32_bf16 v[98:101], v[156:159], v[188:191], v[98:101]
	v_mfma_f32_16x16x32_bf16 v[90:93], v[164:167], v[188:191], v[90:93]
	v_mfma_f32_16x16x32_bf16 v[82:85], v[156:159], v[196:199], v[82:85]
	v_mfma_f32_16x16x32_bf16 v[74:77], v[164:167], v[196:199], v[74:77]
	v_mfma_f32_16x16x32_bf16 v[118:121], v[200:203], v[168:171], v[118:121]
	v_mfma_f32_16x16x32_bf16 v[110:113], v[208:211], v[168:171], v[110:113]
	v_mfma_f32_16x16x32_bf16 v[102:105], v[200:203], v[176:179], v[102:105]
	v_mfma_f32_16x16x32_bf16 v[94:97], v[208:211], v[176:179], v[94:97]
	v_mfma_f32_16x16x32_bf16 v[86:89], v[200:203], v[184:187], v[86:89]
	v_mfma_f32_16x16x32_bf16 v[78:81], v[208:211], v[184:187], v[78:81]
	v_mfma_f32_16x16x32_bf16 v[70:73], v[200:203], v[192:195], v[70:73]
	v_mfma_f32_16x16x32_bf16 v[66:69], v[208:211], v[192:195], v[66:69]
	v_mfma_f32_16x16x32_bf16 v[118:121], v[204:207], v[172:175], v[118:121]
	v_mfma_f32_16x16x32_bf16 v[110:113], v[212:215], v[172:175], v[110:113]
	v_mfma_f32_16x16x32_bf16 v[102:105], v[204:207], v[180:183], v[102:105]
	v_mfma_f32_16x16x32_bf16 v[94:97], v[212:215], v[180:183], v[94:97]
	v_mfma_f32_16x16x32_bf16 v[86:89], v[204:207], v[188:191], v[86:89]
	v_mfma_f32_16x16x32_bf16 v[78:81], v[212:215], v[188:191], v[78:81]
	v_mfma_f32_16x16x32_bf16 v[70:73], v[204:207], v[196:199], v[70:73]
	v_mfma_f32_16x16x32_bf16 v[66:69], v[212:215], v[196:199], v[66:69]
	s_setprio 0
	s_barrier
	ds_read_b128 v[168:171], v149 offset:49152
	ds_read_b128 v[172:175], v149 offset:50176
	ds_read_b128 v[176:179], v149 offset:51200
	ds_read_b128 v[180:183], v149 offset:52224
	ds_read_b128 v[184:187], v149 offset:53248
	ds_read_b128 v[188:191], v149 offset:54272
	ds_read_b128 v[192:195], v149 offset:55296
	ds_read_b128 v[196:199], v149 offset:56320
	s_add_i32 s54, 0, 0x1c000
	s_add_i32 s28, s82, s67
	v_lshl_add_u64 v[144:145], v[144:145], 0, s[22:23]
	s_mov_b32 m0, s28
	s_nop 0
	global_load_lds_dwordx4 v[144:145], off
	v_lshl_add_u64 v[144:145], v[216:217], 0, s[22:23]
	s_add_i32 m0, s28, 0x2000
	s_nop 0
	global_load_lds_dwordx4 v[144:145], off
	s_mov_b32 m0, s72
	v_lshl_add_u64 v[144:145], v[218:219], 0, s[22:23]
	global_load_lds_dwordx4 v[144:145], off
	v_lshl_add_u64 v[144:145], v[220:221], 0, s[22:23]
	s_mov_b32 m0, s73
	s_nop 0
	global_load_lds_dwordx4 v[144:145], off
	s_add_u32 s28, s52, 0x100080
	s_addc_u32 s29, s53, 0
	s_add_i32 s52, s54, s67
	v_lshl_add_u64 v[144:145], s[28:29], 0, v[134:135]
	s_mov_b32 m0, s52
	s_nop 0
	global_load_lds_dwordx4 v[144:145], off
	v_lshl_add_u64 v[144:145], s[28:29], 0, v[130:131]
	s_add_i32 m0, s52, 0x2000
	s_nop 0
	global_load_lds_dwordx4 v[144:145], off
	s_waitcnt vmcnt(8)
	s_waitcnt lgkmcnt(0)
	s_barrier
	s_setprio 1
	v_mfma_f32_16x16x32_bf16 v[62:65], v[152:155], v[168:171], v[62:65]
	v_mfma_f32_16x16x32_bf16 v[58:61], v[160:163], v[168:171], v[58:61]
	v_mfma_f32_16x16x32_bf16 v[54:57], v[152:155], v[176:179], v[54:57]
	v_mfma_f32_16x16x32_bf16 v[46:49], v[160:163], v[176:179], v[46:49]
	v_mfma_f32_16x16x32_bf16 v[38:41], v[152:155], v[184:187], v[38:41]
	v_mfma_f32_16x16x32_bf16 v[30:33], v[160:163], v[184:187], v[30:33]
	v_mfma_f32_16x16x32_bf16 v[22:25], v[152:155], v[192:195], v[22:25]
	v_mfma_f32_16x16x32_bf16 v[14:17], v[160:163], v[192:195], v[14:17]
	v_mfma_f32_16x16x32_bf16 v[62:65], v[156:159], v[172:175], v[62:65]
	v_mfma_f32_16x16x32_bf16 v[58:61], v[164:167], v[172:175], v[58:61]
	v_mfma_f32_16x16x32_bf16 v[54:57], v[156:159], v[180:183], v[54:57]
	v_mfma_f32_16x16x32_bf16 v[46:49], v[164:167], v[180:183], v[46:49]
	v_mfma_f32_16x16x32_bf16 v[38:41], v[156:159], v[188:191], v[38:41]
	v_mfma_f32_16x16x32_bf16 v[30:33], v[164:167], v[188:191], v[30:33]
	v_mfma_f32_16x16x32_bf16 v[22:25], v[156:159], v[196:199], v[22:25]
	v_mfma_f32_16x16x32_bf16 v[14:17], v[164:167], v[196:199], v[14:17]
	v_mfma_f32_16x16x32_bf16 v[50:53], v[200:203], v[168:171], v[50:53]
	v_mfma_f32_16x16x32_bf16 v[42:45], v[208:211], v[168:171], v[42:45]
	v_mfma_f32_16x16x32_bf16 v[34:37], v[200:203], v[176:179], v[34:37]
	v_mfma_f32_16x16x32_bf16 v[26:29], v[208:211], v[176:179], v[26:29]
	v_mfma_f32_16x16x32_bf16 v[18:21], v[200:203], v[184:187], v[18:21]
	v_mfma_f32_16x16x32_bf16 v[10:13], v[208:211], v[184:187], v[10:13]
	v_mfma_f32_16x16x32_bf16 v[6:9], v[200:203], v[192:195], v[6:9]
	v_mfma_f32_16x16x32_bf16 v[2:5], v[208:211], v[192:195], v[2:5]
	v_mfma_f32_16x16x32_bf16 v[50:53], v[204:207], v[172:175], v[50:53]
	v_mfma_f32_16x16x32_bf16 v[42:45], v[212:215], v[172:175], v[42:45]
	v_mfma_f32_16x16x32_bf16 v[34:37], v[204:207], v[180:183], v[34:37]
	v_mfma_f32_16x16x32_bf16 v[26:29], v[212:215], v[180:183], v[26:29]
	v_mfma_f32_16x16x32_bf16 v[18:21], v[204:207], v[188:191], v[18:21]
	v_mfma_f32_16x16x32_bf16 v[10:13], v[212:215], v[188:191], v[10:13]
	v_mfma_f32_16x16x32_bf16 v[6:9], v[204:207], v[196:199], v[6:9]
	v_mfma_f32_16x16x32_bf16 v[2:5], v[212:215], v[196:199], v[2:5]
	s_setprio 0
	s_add_i32 s81, s81, 2
	s_add_u32 s39, s39, 0x100
	s_addc_u32 s41, s41, 0
	s_add_u32 s50, s50, 0x100
	s_addc_u32 s51, s51, 0
	s_cmp_gt_u32 s81, 61
	s_barrier
	s_cbranch_scc0 .LBB0_2485
	v_lshl_add_u32 v152, s48, 8, v1
	v_lshl_or_b32 v144, s80, 8, v147
	v_ashrrev_i32_e32 v153, 31, v152
	v_ashrrev_i32_e32 v145, 31, v144
	v_lshlrev_b64 v[154:155], 13, v[152:153]
	v_lshl_add_u64 v[154:155], s[18:19], 0, v[154:155]
	v_lshlrev_b64 v[156:157], 1, v[144:145]
	v_lshl_add_u64 v[144:145], v[154:155], 0, v[156:157]
	v_cvt_pk_bf16_f32 v126, v126, v127
	v_cvt_pk_bf16_f32 v127, v128, v129
	v_cvt_pk_bf16_f32 v128, v122, v123
	v_cvt_pk_bf16_f32 v129, v124, v125
	global_store_dwordx4 v[144:145], v[126:129], off
	v_cvt_pk_bf16_f32 v118, v118, v119
	v_cvt_pk_bf16_f32 v119, v120, v121
	v_cvt_pk_bf16_f32 v120, v110, v111
	v_or_b32_e32 v110, 16, v152
	v_ashrrev_i32_e32 v111, 31, v110
	v_lshlrev_b64 v[110:111], 13, v[110:111]
	v_lshl_add_u64 v[110:111], s[18:19], 0, v[110:111]
	v_cvt_pk_bf16_f32 v121, v112, v113
	global_store_dwordx4 v[144:145], v[118:121], off offset:256
	s_mov_b32 s48, s40
	s_mov_b32 s80, s38
	v_lshl_add_u64 v[118:119], v[110:111], 0, v[156:157]
	v_cvt_pk_bf16_f32 v110, v114, v115
	v_cvt_pk_bf16_f32 v111, v116, v117
	v_cvt_pk_bf16_f32 v112, v106, v107
	v_cvt_pk_bf16_f32 v113, v108, v109
	global_store_dwordx4 v[118:119], v[110:113], off
	v_cvt_pk_bf16_f32 v102, v102, v103
	v_cvt_pk_bf16_f32 v103, v104, v105
	v_cvt_pk_bf16_f32 v104, v94, v95
	v_or_b32_e32 v94, 32, v152
	v_ashrrev_i32_e32 v95, 31, v94
	v_lshlrev_b64 v[94:95], 13, v[94:95]
	v_lshl_add_u64 v[94:95], s[18:19], 0, v[94:95]
	v_cvt_pk_bf16_f32 v105, v96, v97
	global_store_dwordx4 v[118:119], v[102:105], off offset:256
	s_mov_b64 s[52:53], s[46:47]
	s_mov_b64 s[50:51], s[44:45]
	v_lshl_add_u64 v[102:103], v[94:95], 0, v[156:157]
	v_cvt_pk_bf16_f32 v94, v98, v99
	v_cvt_pk_bf16_f32 v95, v100, v101
	v_cvt_pk_bf16_f32 v96, v90, v91
	v_cvt_pk_bf16_f32 v97, v92, v93
	global_store_dwordx4 v[102:103], v[94:97], off
	v_cvt_pk_bf16_f32 v86, v86, v87
	v_cvt_pk_bf16_f32 v87, v88, v89
	v_cvt_pk_bf16_f32 v88, v78, v79
	v_or_b32_e32 v78, 48, v152
	v_ashrrev_i32_e32 v79, 31, v78
	v_lshlrev_b64 v[78:79], 13, v[78:79]
	v_lshl_add_u64 v[78:79], s[18:19], 0, v[78:79]
	v_cvt_pk_bf16_f32 v89, v80, v81
	global_store_dwordx4 v[102:103], v[86:89], off offset:256
	s_nop 1
	v_lshl_add_u64 v[86:87], v[78:79], 0, v[156:157]
	v_cvt_pk_bf16_f32 v78, v82, v83
	v_cvt_pk_bf16_f32 v79, v84, v85
	v_cvt_pk_bf16_f32 v80, v74, v75
	v_cvt_pk_bf16_f32 v81, v76, v77
	global_store_dwordx4 v[86:87], v[78:81], off
	v_cvt_pk_bf16_f32 v70, v70, v71
	v_cvt_pk_bf16_f32 v71, v72, v73
	v_cvt_pk_bf16_f32 v72, v66, v67
	v_cvt_pk_bf16_f32 v73, v68, v69
	global_store_dwordx4 v[86:87], v[70:73], off offset:256
	v_cvt_pk_bf16_f32 v62, v62, v63
	v_cvt_pk_bf16_f32 v63, v64, v65
	v_cvt_pk_bf16_f32 v64, v58, v59
	v_add_co_u32_e32 v58, vcc, s76, v144
	v_lshl_add_u64 v[66:67], v[144:145], 0, s[20:21]
	s_nop 0
	v_addc_co_u32_e32 v59, vcc, 0, v145, vcc
	v_cvt_pk_bf16_f32 v65, v60, v61
	global_store_dwordx4 v[58:59], v[62:65], off
	v_cvt_pk_bf16_f32 v50, v50, v51
	v_cvt_pk_bf16_f32 v51, v52, v53
	v_cvt_pk_bf16_f32 v52, v42, v43
	v_cvt_pk_bf16_f32 v53, v44, v45
	global_store_dwordx4 v[66:67], v[50:53], off offset:256
	v_cvt_pk_bf16_f32 v42, v54, v55
	v_cvt_pk_bf16_f32 v43, v56, v57
	v_cvt_pk_bf16_f32 v44, v46, v47
	v_add_co_u32_e32 v46, vcc, s77, v144
	s_nop 0
	v_lshl_add_u64 v[50:51], v[144:145], 0, s[26:27]
	v_addc_co_u32_e32 v47, vcc, 0, v145, vcc
	v_cvt_pk_bf16_f32 v45, v48, v49
	global_store_dwordx4 v[46:47], v[42:45], off
	v_cvt_pk_bf16_f32 v34, v34, v35
	v_cvt_pk_bf16_f32 v35, v36, v37
	v_cvt_pk_bf16_f32 v36, v26, v27
	v_cvt_pk_bf16_f32 v37, v28, v29
	global_store_dwordx4 v[50:51], v[34:37], off offset:256
	v_cvt_pk_bf16_f32 v26, v38, v39
	v_cvt_pk_bf16_f32 v27, v40, v41
	v_cvt_pk_bf16_f32 v28, v30, v31
	v_add_co_u32_e32 v30, vcc, s78, v144
	s_nop 0
	v_lshl_add_u64 v[34:35], v[144:145], 0, s[34:35]
	v_addc_co_u32_e32 v31, vcc, 0, v145, vcc
	v_cvt_pk_bf16_f32 v29, v32, v33
	global_store_dwordx4 v[30:31], v[26:29], off
	v_cvt_pk_bf16_f32 v18, v18, v19
	v_cvt_pk_bf16_f32 v19, v20, v21
	v_cvt_pk_bf16_f32 v20, v10, v11
	v_cvt_pk_bf16_f32 v21, v12, v13
	global_store_dwordx4 v[34:35], v[18:21], off offset:256
	v_cvt_pk_bf16_f32 v10, v22, v23
	v_cvt_pk_bf16_f32 v11, v24, v25
	v_cvt_pk_bf16_f32 v12, v14, v15
	v_add_co_u32_e32 v14, vcc, s79, v144
	s_nop 0
	v_lshl_add_u64 v[18:19], v[144:145], 0, s[36:37]
	v_addc_co_u32_e32 v15, vcc, 0, v145, vcc
	s_and_b64 vcc, exec, s[6:7]
	v_cvt_pk_bf16_f32 v13, v16, v17
	global_store_dwordx4 v[14:15], v[10:13], off
	v_cvt_pk_bf16_f32 v6, v6, v7
	v_cvt_pk_bf16_f32 v7, v8, v9
	v_cvt_pk_bf16_f32 v8, v2, v3
	v_cvt_pk_bf16_f32 v9, v4, v5
	global_store_dwordx4 v[18:19], v[6:9], off offset:256
	s_cbranch_vccz .LBB0_2478
	s_waitcnt vmcnt(0)
	s_cmpk_gt_u32 s66, 0xff
	s_cbranch_scc1 .LBB0_2489
	s_barrier

.LBB0_3027:
	s_cmp_eq_u32 s22, 56
	s_cselect_b32 s14, 2, 0
	s_and_b64 s[6:7], s[6:7], exec
	s_cselect_b32 s70, 1, s14
	s_lshl_b32 s6, s13, 5
	s_and_b32 s13, s6, 0x60
	s_mov_b64 s[6:7], 0x80
	s_add_i32 m0, s23, 0x18000
	v_lshl_add_u64 v[8:9], v[8:9], 0, s[6:7]
	s_ashr_i32 s57, s24, 31
	s_ashr_i32 s58, s2, 31
	s_lshl_b32 s16, s12, 13
	s_lshl_b32 s17, s13, 7
	s_waitcnt vmcnt(0)
	s_barrier
	global_load_lds_dwordx4 v[8:9], off
	v_lshl_add_u64 v[6:7], v[6:7], 0, s[6:7]
	s_add_i32 m0, s23, 0x1a000
	s_add_i32 s59, s23, 0x8000
	s_add_i32 s60, s23, 0xa000
	global_load_lds_dwordx4 v[6:7], off
	v_lshl_add_u64 v[4:5], v[4:5], 0, s[6:7]
	s_mov_b32 m0, s59
	s_add_u32 s14, s38, 0x100080
	global_load_lds_dwordx4 v[4:5], off
	v_lshl_add_u64 v[2:3], v[2:3], 0, s[6:7]
	s_mov_b32 m0, s60
	s_addc_u32 s15, s39, 0
	global_load_lds_dwordx4 v[2:3], off
	s_add_i32 m0, s23, 0x1c000
	v_lshl_add_u64 v[2:3], s[14:15], 0, v[134:135]
	global_load_lds_dwordx4 v[2:3], off
	v_lshl_add_u64 v[2:3], s[14:15], 0, v[130:131]
	s_add_i32 m0, s23, 0x1e000
	s_add_u32 s62, s9, 0xfde00000
	global_load_lds_dwordx4 v[2:3], off
	v_lshrrev_b32_e32 v3, 1, v10
	v_and_b32_e32 v3, 24, v3
	v_and_b32_e32 v2, 15, v10
	v_lshlrev_b32_e32 v4, 1, v3
	v_lshl_or_b32 v1, s12, 6, v2
	v_lshl_or_b32 v2, v2, 6, v4
	v_lshlrev_b32_e32 v4, 2, v10
	v_and_b32_e32 v4, 32, v4
	v_or_b32_e32 v149, s13, v3
	v_bitop3_b32 v5, v2, s16, v4 bitop3:0xde
	v_bitop3_b32 v148, v2, s17, v4 bitop3:0xde
	v_lshlrev_b32_e32 v2, 2, v149
	v_mov_b32_e32 v3, v135
	v_lshl_add_u64 v[138:139], s[4:5], 0, v[2:3]
	v_lshlrev_b32_e32 v2, 16, v11
	v_and_b32_e32 v2, 0xfffe0000, v2
	v_lshl_add_u32 v2, v12, 13, v2
	v_and_b32_e32 v3, 1, v11
	v_lshl_or_b32 v2, v3, 6, v2
	v_lshl_add_u32 v140, v13, 1, v2
	v_lshlrev_b32_e32 v2, 16, v15
	v_and_b32_e32 v2, 0xfffe0000, v2
	s_waitcnt vmcnt(6)
	v_lshl_add_u32 v2, v14, 13, v2
	v_and_b32_e32 v3, 1, v15
	s_addc_u32 s63, s8, -1
	v_lshl_or_b32 v2, v3, 6, v2
	s_add_i32 s64, 0, 0x10000
	s_add_i32 s65, 0, 0x14000
	s_mov_b32 s61, 0
	v_mov_b32_e32 v141, v135
	v_lshl_add_u32 v142, v16, 1, v2
	v_mov_b32_e32 v143, v135
	v_mov_b64_e32 v[144:145], 0x73d
	v_add_u32_e32 v150, s64, v148
	v_add_u32_e32 v151, 0, v5
	v_add_u32_e32 v152, s65, v148
	s_mov_b64 s[8:9], 0x20000
	s_mov_b32 s66, 0x20000
	s_mov_b64 s[12:13], 0x24000
	s_mov_b32 s67, 0x24000
	s_mov_b64 s[14:15], 0x28000
	s_mov_b32 s68, 0x28000
	s_mov_b64 s[16:17], 0x2c000
	s_movk_i32 s69, 0x3900
	s_mov_b64 s[36:37], s[40:41]
	s_mov_b64 s[34:35], s[38:39]
	s_barrier
	s_branch .LBB0_3029

.LBB0_3048:
	ds_read_b128 v[154:157], v150
	ds_read_b128 v[158:161], v150 offset:1024
	ds_read_b128 v[162:165], v150 offset:2048
	ds_read_b128 v[166:169], v150 offset:3072
	ds_read_b128 v[202:205], v152
	ds_read_b128 v[206:209], v152 offset:1024
	ds_read_b128 v[210:213], v152 offset:2048
	ds_read_b128 v[214:217], v152 offset:3072
	s_add_u32 s28, s38, 0xfff00080
	s_addc_u32 s29, s39, -1
	s_cmp_eq_u32 s72, 60
	s_cselect_b32 s45, s37, s29
	s_cselect_b32 s44, s36, s28
	s_cselect_b32 s41, s35, s71
	s_cselect_b32 s40, s34, s21
	v_lshl_add_u64 v[146:147], s[38:39], 0, v[142:143]
	s_add_i32 m0, s23, 0xc000
	ds_read_b128 v[170:173], v151
	ds_read_b128 v[174:177], v151 offset:1024
	ds_read_b128 v[178:181], v151 offset:2048
	ds_read_b128 v[182:185], v151 offset:3072
	ds_read_b128 v[186:189], v151 offset:4096
	ds_read_b128 v[190:193], v151 offset:5120
	ds_read_b128 v[194:197], v151 offset:6144
	ds_read_b128 v[198:201], v151 offset:7168
	global_load_lds_dwordx4 v[146:147], off
	v_lshl_add_u64 v[146:147], s[38:39], 0, v[140:141]
	s_add_i32 m0, s23, 0xe000
	s_nop 0
	global_load_lds_dwordx4 v[146:147], off
	s_waitcnt vmcnt(8)
	s_waitcnt lgkmcnt(0)
	s_barrier
	s_setprio 1
	v_mfma_f32_16x16x32_bf16 v[126:129], v[154:157], v[170:173], v[126:129]
	v_mfma_f32_16x16x32_bf16 v[122:125], v[162:165], v[170:173], v[122:125]
	v_mfma_f32_16x16x32_bf16 v[118:121], v[154:157], v[178:181], v[118:121]
	v_mfma_f32_16x16x32_bf16 v[110:113], v[162:165], v[178:181], v[110:113]
	v_mfma_f32_16x16x32_bf16 v[102:105], v[154:157], v[186:189], v[102:105]
	v_mfma_f32_16x16x32_bf16 v[94:97], v[162:165], v[186:189], v[94:97]
	v_mfma_f32_16x16x32_bf16 v[86:89], v[154:157], v[194:197], v[86:89]
	v_mfma_f32_16x16x32_bf16 v[78:81], v[162:165], v[194:197], v[78:81]
	v_mfma_f32_16x16x32_bf16 v[126:129], v[158:161], v[174:177], v[126:129]
	v_mfma_f32_16x16x32_bf16 v[122:125], v[166:169], v[174:177], v[122:125]
	v_mfma_f32_16x16x32_bf16 v[118:121], v[158:161], v[182:185], v[118:121]
	v_mfma_f32_16x16x32_bf16 v[110:113], v[166:169], v[182:185], v[110:113]
	v_mfma_f32_16x16x32_bf16 v[102:105], v[158:161], v[190:193], v[102:105]
	v_mfma_f32_16x16x32_bf16 v[94:97], v[166:169], v[190:193], v[94:97]
	v_mfma_f32_16x16x32_bf16 v[86:89], v[158:161], v[198:201], v[86:89]
	v_mfma_f32_16x16x32_bf16 v[78:81], v[166:169], v[198:201], v[78:81]
	v_mfma_f32_16x16x32_bf16 v[114:117], v[202:205], v[170:173], v[114:117]
	v_mfma_f32_16x16x32_bf16 v[106:109], v[210:213], v[170:173], v[106:109]
	v_mfma_f32_16x16x32_bf16 v[98:101], v[202:205], v[178:181], v[98:101]
	v_mfma_f32_16x16x32_bf16 v[90:93], v[210:213], v[178:181], v[90:93]
	v_mfma_f32_16x16x32_bf16 v[82:85], v[202:205], v[186:189], v[82:85]
	v_mfma_f32_16x16x32_bf16 v[74:77], v[210:213], v[186:189], v[74:77]
	v_mfma_f32_16x16x32_bf16 v[70:73], v[202:205], v[194:197], v[70:73]
	v_mfma_f32_16x16x32_bf16 v[66:69], v[210:213], v[194:197], v[66:69]
	v_mfma_f32_16x16x32_bf16 v[114:117], v[206:209], v[174:177], v[114:117]
	v_mfma_f32_16x16x32_bf16 v[106:109], v[214:217], v[174:177], v[106:109]
	v_mfma_f32_16x16x32_bf16 v[98:101], v[206:209], v[182:185], v[98:101]
	v_mfma_f32_16x16x32_bf16 v[90:93], v[214:217], v[182:185], v[90:93]
	v_mfma_f32_16x16x32_bf16 v[82:85], v[206:209], v[190:193], v[82:85]
	v_mfma_f32_16x16x32_bf16 v[74:77], v[214:217], v[190:193], v[74:77]
	v_mfma_f32_16x16x32_bf16 v[70:73], v[206:209], v[198:201], v[70:73]
	v_mfma_f32_16x16x32_bf16 v[66:69], v[214:217], v[198:201], v[66:69]
	s_setprio 0
	s_barrier
	ds_read_b128 v[170:173], v151 offset:16384
	ds_read_b128 v[174:177], v151 offset:17408
	ds_read_b128 v[178:181], v151 offset:18432
	ds_read_b128 v[182:185], v151 offset:19456
	ds_read_b128 v[186:189], v151 offset:20480
	ds_read_b128 v[190:193], v151 offset:21504
	ds_read_b128 v[194:197], v151 offset:22528
	ds_read_b128 v[198:201], v151 offset:23552
	s_add_i32 s28, s64, s54
	v_lshl_add_u64 v[146:147], s[40:41], 0, v[134:135]
	s_mov_b32 m0, s28
	s_nop 0
	global_load_lds_dwordx4 v[146:147], off
	v_lshl_add_u64 v[218:219], s[40:41], 0, v[130:131]
	s_add_i32 m0, s28, 0x2000
	s_nop 0
	global_load_lds_dwordx4 v[218:219], off
	s_mov_b32 m0, s23
	v_lshl_add_u64 v[220:221], s[44:45], 0, v[136:137]
	global_load_lds_dwordx4 v[220:221], off
	v_lshl_add_u64 v[222:223], s[44:45], 0, v[132:133]
	s_mov_b32 m0, s27
	s_nop 0
	global_load_lds_dwordx4 v[222:223], off
	s_add_u32 s28, s40, 0x100000
	s_addc_u32 s29, s41, 0
	s_add_i32 s73, s65, s54
	v_lshl_add_u64 v[226:227], s[28:29], 0, v[134:135]
	s_mov_b32 m0, s73
	s_nop 0
	global_load_lds_dwordx4 v[226:227], off
	v_lshl_add_u64 v[226:227], s[28:29], 0, v[130:131]
	s_add_i32 m0, s73, 0x2000
	s_nop 0
	global_load_lds_dwordx4 v[226:227], off
	s_waitcnt vmcnt(8)
	s_waitcnt lgkmcnt(0)
	s_barrier
	s_setprio 1
	v_mfma_f32_16x16x32_bf16 v[62:65], v[154:157], v[170:173], v[62:65]
	v_mfma_f32_16x16x32_bf16 v[58:61], v[162:165], v[170:173], v[58:61]
	v_mfma_f32_16x16x32_bf16 v[54:57], v[154:157], v[178:181], v[54:57]
	v_mfma_f32_16x16x32_bf16 v[46:49], v[162:165], v[178:181], v[46:49]
	v_mfma_f32_16x16x32_bf16 v[38:41], v[154:157], v[186:189], v[38:41]
	v_mfma_f32_16x16x32_bf16 v[30:33], v[162:165], v[186:189], v[30:33]
	v_mfma_f32_16x16x32_bf16 v[22:25], v[154:157], v[194:197], v[22:25]
	v_mfma_f32_16x16x32_bf16 v[14:17], v[162:165], v[194:197], v[14:17]
	v_mfma_f32_16x16x32_bf16 v[62:65], v[158:161], v[174:177], v[62:65]
	v_mfma_f32_16x16x32_bf16 v[58:61], v[166:169], v[174:177], v[58:61]
	v_mfma_f32_16x16x32_bf16 v[54:57], v[158:161], v[182:185], v[54:57]
	v_mfma_f32_16x16x32_bf16 v[46:49], v[166:169], v[182:185], v[46:49]
	v_mfma_f32_16x16x32_bf16 v[38:41], v[158:161], v[190:193], v[38:41]
	v_mfma_f32_16x16x32_bf16 v[30:33], v[166:169], v[190:193], v[30:33]
	v_mfma_f32_16x16x32_bf16 v[22:25], v[158:161], v[198:201], v[22:25]
	v_mfma_f32_16x16x32_bf16 v[14:17], v[166:169], v[198:201], v[14:17]
	v_mfma_f32_16x16x32_bf16 v[50:53], v[202:205], v[170:173], v[50:53]
	v_mfma_f32_16x16x32_bf16 v[42:45], v[210:213], v[170:173], v[42:45]
	v_mfma_f32_16x16x32_bf16 v[34:37], v[202:205], v[178:181], v[34:37]
	v_mfma_f32_16x16x32_bf16 v[26:29], v[210:213], v[178:181], v[26:29]
	v_mfma_f32_16x16x32_bf16 v[18:21], v[202:205], v[186:189], v[18:21]
	v_mfma_f32_16x16x32_bf16 v[10:13], v[210:213], v[186:189], v[10:13]
	v_mfma_f32_16x16x32_bf16 v[6:9], v[202:205], v[194:197], v[6:9]
	v_mfma_f32_16x16x32_bf16 v[2:5], v[210:213], v[194:197], v[2:5]
	v_mfma_f32_16x16x32_bf16 v[50:53], v[206:209], v[174:177], v[50:53]
	v_mfma_f32_16x16x32_bf16 v[42:45], v[214:217], v[174:177], v[42:45]
	v_mfma_f32_16x16x32_bf16 v[34:37], v[206:209], v[182:185], v[34:37]
	v_mfma_f32_16x16x32_bf16 v[26:29], v[214:217], v[182:185], v[26:29]
	v_mfma_f32_16x16x32_bf16 v[18:21], v[206:209], v[190:193], v[18:21]
	v_mfma_f32_16x16x32_bf16 v[10:13], v[214:217], v[190:193], v[10:13]
	v_mfma_f32_16x16x32_bf16 v[6:9], v[206:209], v[198:201], v[6:9]
	v_mfma_f32_16x16x32_bf16 v[2:5], v[214:217], v[198:201], v[2:5]
	s_setprio 0
	s_add_i32 s73, 0, 0x18000
	v_add_u32_e32 v153, s73, v148
	s_barrier
	ds_read_b128 v[154:157], v153
	ds_read_b128 v[158:161], v153 offset:1024
	ds_read_b128 v[162:165], v153 offset:2048
	ds_read_b128 v[166:169], v153 offset:3072
	ds_read_b128 v[202:205], v153 offset:16384
	ds_read_b128 v[206:209], v153 offset:17408
	ds_read_b128 v[210:213], v153 offset:18432
	ds_read_b128 v[214:217], v153 offset:19456
	s_add_u32 s28, s44, 0x100000
	s_addc_u32 s29, s45, 0
	s_mov_b32 m0, s55
	v_lshl_add_u64 v[226:227], s[28:29], 0, v[136:137]
	ds_read_b128 v[170:173], v151 offset:32768
	ds_read_b128 v[174:177], v151 offset:33792
	ds_read_b128 v[178:181], v151 offset:34816
	ds_read_b128 v[182:185], v151 offset:35840
	ds_read_b128 v[186:189], v151 offset:36864
	ds_read_b128 v[190:193], v151 offset:37888
	ds_read_b128 v[194:197], v151 offset:38912
	ds_read_b128 v[198:201], v151 offset:39936
	global_load_lds_dwordx4 v[226:227], off
	v_lshl_add_u64 v[226:227], s[28:29], 0, v[132:133]
	s_mov_b32 m0, s56
	s_nop 0
	global_load_lds_dwordx4 v[226:227], off
	s_waitcnt vmcnt(8)
	s_waitcnt lgkmcnt(0)
	s_barrier
	s_setprio 1
	v_mfma_f32_16x16x32_bf16 v[126:129], v[154:157], v[170:173], v[126:129]
	v_mfma_f32_16x16x32_bf16 v[122:125], v[162:165], v[170:173], v[122:125]
	v_mfma_f32_16x16x32_bf16 v[118:121], v[154:157], v[178:181], v[118:121]
	v_mfma_f32_16x16x32_bf16 v[110:113], v[162:165], v[178:181], v[110:113]
	v_mfma_f32_16x16x32_bf16 v[102:105], v[154:157], v[186:189], v[102:105]
	v_mfma_f32_16x16x32_bf16 v[94:97], v[162:165], v[186:189], v[94:97]
	v_mfma_f32_16x16x32_bf16 v[86:89], v[154:157], v[194:197], v[86:89]
	v_mfma_f32_16x16x32_bf16 v[78:81], v[162:165], v[194:197], v[78:81]
	v_mfma_f32_16x16x32_bf16 v[126:129], v[158:161], v[174:177], v[126:129]
	v_mfma_f32_16x16x32_bf16 v[122:125], v[166:169], v[174:177], v[122:125]
	v_mfma_f32_16x16x32_bf16 v[118:121], v[158:161], v[182:185], v[118:121]
	v_mfma_f32_16x16x32_bf16 v[110:113], v[166:169], v[182:185], v[110:113]
	v_mfma_f32_16x16x32_bf16 v[102:105], v[158:161], v[190:193], v[102:105]
	v_mfma_f32_16x16x32_bf16 v[94:97], v[166:169], v[190:193], v[94:97]
	v_mfma_f32_16x16x32_bf16 v[86:89], v[158:161], v[198:201], v[86:89]
	v_mfma_f32_16x16x32_bf16 v[78:81], v[166:169], v[198:201], v[78:81]
	v_mfma_f32_16x16x32_bf16 v[114:117], v[202:205], v[170:173], v[114:117]
	v_mfma_f32_16x16x32_bf16 v[106:109], v[210:213], v[170:173], v[106:109]
	v_mfma_f32_16x16x32_bf16 v[98:101], v[202:205], v[178:181], v[98:101]
	v_mfma_f32_16x16x32_bf16 v[90:93], v[210:213], v[178:181], v[90:93]
	v_mfma_f32_16x16x32_bf16 v[82:85], v[202:205], v[186:189], v[82:85]
	v_mfma_f32_16x16x32_bf16 v[74:77], v[210:213], v[186:189], v[74:77]
	v_mfma_f32_16x16x32_bf16 v[70:73], v[202:205], v[194:197], v[70:73]
	v_mfma_f32_16x16x32_bf16 v[66:69], v[210:213], v[194:197], v[66:69]
	v_mfma_f32_16x16x32_bf16 v[114:117], v[206:209], v[174:177], v[114:117]
	v_mfma_f32_16x16x32_bf16 v[106:109], v[214:217], v[174:177], v[106:109]
	v_mfma_f32_16x16x32_bf16 v[98:101], v[206:209], v[182:185], v[98:101]
	v_mfma_f32_16x16x32_bf16 v[90:93], v[214:217], v[182:185], v[90:93]
	v_mfma_f32_16x16x32_bf16 v[82:85], v[206:209], v[190:193], v[82:85]
	v_mfma_f32_16x16x32_bf16 v[74:77], v[214:217], v[190:193], v[74:77]
	v_mfma_f32_16x16x32_bf16 v[70:73], v[206:209], v[198:201], v[70:73]
	v_mfma_f32_16x16x32_bf16 v[66:69], v[214:217], v[198:201], v[66:69]
	s_setprio 0
	s_barrier
	ds_read_b128 v[170:173], v151 offset:49152
	ds_read_b128 v[174:177], v151 offset:50176
	ds_read_b128 v[178:181], v151 offset:51200
	ds_read_b128 v[182:185], v151 offset:52224
	ds_read_b128 v[186:189], v151 offset:53248
	ds_read_b128 v[190:193], v151 offset:54272
	ds_read_b128 v[194:197], v151 offset:55296
	ds_read_b128 v[198:201], v151 offset:56320
	s_add_i32 s44, 0, 0x1c000
	s_add_i32 s28, s73, s54
	v_lshl_add_u64 v[146:147], v[146:147], 0, s[6:7]
	s_mov_b32 m0, s28
	s_nop 0
	global_load_lds_dwordx4 v[146:147], off
	v_lshl_add_u64 v[146:147], v[218:219], 0, s[6:7]
	s_add_i32 m0, s28, 0x2000
	s_nop 0
	global_load_lds_dwordx4 v[146:147], off
	s_mov_b32 m0, s59
	v_lshl_add_u64 v[146:147], v[220:221], 0, s[6:7]
	global_load_lds_dwordx4 v[146:147], off
	v_lshl_add_u64 v[146:147], v[222:223], 0, s[6:7]
	s_mov_b32 m0, s60
	s_nop 0
	global_load_lds_dwordx4 v[146:147], off
	s_add_u32 s28, s40, 0x100080
	s_addc_u32 s29, s41, 0
	s_add_i32 s40, s44, s54
	v_lshl_add_u64 v[146:147], s[28:29], 0, v[134:135]
	s_mov_b32 m0, s40
	s_nop 0
	global_load_lds_dwordx4 v[146:147], off
	v_lshl_add_u64 v[146:147], s[28:29], 0, v[130:131]
	s_add_i32 m0, s40, 0x2000
	s_nop 0
	global_load_lds_dwordx4 v[146:147], off
	s_waitcnt vmcnt(8)
	s_waitcnt lgkmcnt(0)
	s_barrier
	s_setprio 1
	v_mfma_f32_16x16x32_bf16 v[62:65], v[154:157], v[170:173], v[62:65]
	v_mfma_f32_16x16x32_bf16 v[58:61], v[162:165], v[170:173], v[58:61]
	v_mfma_f32_16x16x32_bf16 v[54:57], v[154:157], v[178:181], v[54:57]
	v_mfma_f32_16x16x32_bf16 v[46:49], v[162:165], v[178:181], v[46:49]
	v_mfma_f32_16x16x32_bf16 v[38:41], v[154:157], v[186:189], v[38:41]
	v_mfma_f32_16x16x32_bf16 v[30:33], v[162:165], v[186:189], v[30:33]
	v_mfma_f32_16x16x32_bf16 v[22:25], v[154:157], v[194:197], v[22:25]
	v_mfma_f32_16x16x32_bf16 v[14:17], v[162:165], v[194:197], v[14:17]
	v_mfma_f32_16x16x32_bf16 v[62:65], v[158:161], v[174:177], v[62:65]
	v_mfma_f32_16x16x32_bf16 v[58:61], v[166:169], v[174:177], v[58:61]
	v_mfma_f32_16x16x32_bf16 v[54:57], v[158:161], v[182:185], v[54:57]
	v_mfma_f32_16x16x32_bf16 v[46:49], v[166:169], v[182:185], v[46:49]
	v_mfma_f32_16x16x32_bf16 v[38:41], v[158:161], v[190:193], v[38:41]
	v_mfma_f32_16x16x32_bf16 v[30:33], v[166:169], v[190:193], v[30:33]
	v_mfma_f32_16x16x32_bf16 v[22:25], v[158:161], v[198:201], v[22:25]
	v_mfma_f32_16x16x32_bf16 v[14:17], v[166:169], v[198:201], v[14:17]
	v_mfma_f32_16x16x32_bf16 v[50:53], v[202:205], v[170:173], v[50:53]
	v_mfma_f32_16x16x32_bf16 v[42:45], v[210:213], v[170:173], v[42:45]
	v_mfma_f32_16x16x32_bf16 v[34:37], v[202:205], v[178:181], v[34:37]
	v_mfma_f32_16x16x32_bf16 v[26:29], v[210:213], v[178:181], v[26:29]
	v_mfma_f32_16x16x32_bf16 v[18:21], v[202:205], v[186:189], v[18:21]
	v_mfma_f32_16x16x32_bf16 v[10:13], v[210:213], v[186:189], v[10:13]
	v_mfma_f32_16x16x32_bf16 v[6:9], v[202:205], v[194:197], v[6:9]
	v_mfma_f32_16x16x32_bf16 v[2:5], v[210:213], v[194:197], v[2:5]
	v_mfma_f32_16x16x32_bf16 v[50:53], v[206:209], v[174:177], v[50:53]
	v_mfma_f32_16x16x32_bf16 v[42:45], v[214:217], v[174:177], v[42:45]
	v_mfma_f32_16x16x32_bf16 v[34:37], v[206:209], v[182:185], v[34:37]
	v_mfma_f32_16x16x32_bf16 v[26:29], v[214:217], v[182:185], v[26:29]
	v_mfma_f32_16x16x32_bf16 v[18:21], v[206:209], v[190:193], v[18:21]
	v_mfma_f32_16x16x32_bf16 v[10:13], v[214:217], v[190:193], v[10:13]
	v_mfma_f32_16x16x32_bf16 v[6:9], v[206:209], v[198:201], v[6:9]
	v_mfma_f32_16x16x32_bf16 v[2:5], v[214:217], v[198:201], v[2:5]
	s_setprio 0
	s_add_i32 s72, s72, 2
	s_add_u32 s21, s21, 0x100
	s_addc_u32 s71, s71, 0
	s_add_u32 s38, s38, 0x100
	s_addc_u32 s39, s39, 0
	s_cmp_gt_u32 s72, 61
	s_barrier
	s_cbranch_scc0 .LBB0_3048
	s_cmp_lt_i32 s70, 2
	s_cbranch_scc1 .LBB0_3053
	s_cmp_eq_u32 s70, 2
	s_mov_b64 s[38:39], -1
	s_cbranch_scc0 .LBB0_3052
	v_lshl_add_u32 v146, s26, 8, v1
	v_or_b32_e32 v156, 16, v146
	v_ashrrev_i32_e32 v147, 31, v146
	v_ashrrev_i32_e32 v157, 31, v156
	v_lshlrev_b64 v[154:155], 10, v[146:147]
	v_lshlrev_b64 v[156:157], 10, v[156:157]
	v_lshl_add_u64 v[154:155], v[138:139], 0, v[154:155]
	v_lshl_add_u64 v[156:157], v[138:139], 0, v[156:157]
	global_store_dwordx4 v[154:155], v[126:129], off
	global_store_dwordx4 v[154:155], v[122:125], off offset:16
	global_store_dwordx4 v[154:155], v[114:117], off offset:512
	global_store_dwordx4 v[154:155], v[106:109], off offset:528
	global_store_dwordx4 v[156:157], v[118:121], off
	global_store_dwordx4 v[156:157], v[110:113], off offset:16
	global_store_dwordx4 v[156:157], v[98:101], off offset:512
	global_store_dwordx4 v[156:157], v[90:93], off offset:528
	v_or_b32_e32 v156, 32, v146
	v_ashrrev_i32_e32 v157, 31, v156
	v_lshlrev_b64 v[156:157], 10, v[156:157]
	v_or_b32_e32 v146, 48, v146
	v_lshl_add_u64 v[156:157], v[138:139], 0, v[156:157]
	v_ashrrev_i32_e32 v147, 31, v146
	global_store_dwordx4 v[156:157], v[102:105], off
	global_store_dwordx4 v[156:157], v[94:97], off offset:16
	global_store_dwordx4 v[156:157], v[82:85], off offset:512
	global_store_dwordx4 v[156:157], v[74:77], off offset:528
	v_lshlrev_b64 v[146:147], 10, v[146:147]
	v_add_co_u32_e32 v156, vcc, s66, v154
	v_lshl_add_u64 v[146:147], v[138:139], 0, v[146:147]
	s_nop 0
	v_addc_co_u32_e32 v157, vcc, 0, v155, vcc
	global_store_dwordx4 v[146:147], v[86:89], off
	global_store_dwordx4 v[146:147], v[78:81], off offset:16
	global_store_dwordx4 v[146:147], v[70:73], off offset:512
	global_store_dwordx4 v[146:147], v[66:69], off offset:528
	v_lshl_add_u64 v[146:147], v[154:155], 0, s[8:9]
	global_store_dwordx4 v[156:157], v[62:65], off
	global_store_dwordx4 v[146:147], v[58:61], off offset:16
	global_store_dwordx4 v[146:147], v[50:53], off offset:512
	global_store_dwordx4 v[146:147], v[42:45], off offset:528
	v_add_co_u32_e32 v156, vcc, s67, v154
	v_lshl_add_u64 v[146:147], v[154:155], 0, s[12:13]
	s_nop 0
	v_addc_co_u32_e32 v157, vcc, 0, v155, vcc
	global_store_dwordx4 v[156:157], v[54:57], off
	global_store_dwordx4 v[146:147], v[46:49], off offset:16
	global_store_dwordx4 v[146:147], v[34:37], off offset:512
	global_store_dwordx4 v[146:147], v[26:29], off offset:528
	v_add_co_u32_e32 v156, vcc, s68, v154
	v_lshl_add_u64 v[146:147], v[154:155], 0, s[14:15]
	s_nop 0
	v_addc_co_u32_e32 v157, vcc, 0, v155, vcc
	global_store_dwordx4 v[156:157], v[38:41], off
	global_store_dwordx4 v[146:147], v[30:33], off offset:16
	global_store_dwordx4 v[146:147], v[18:21], off offset:512
	global_store_dwordx4 v[146:147], v[10:13], off offset:528
	v_lshl_add_u64 v[146:147], v[154:155], 0, s[16:17]
	v_add_co_u32_e32 v154, vcc, 0x2c000, v154
	s_mov_b64 s[38:39], 0
	s_nop 0
	v_addc_co_u32_e32 v155, vcc, 0, v155, vcc
	global_store_dwordx4 v[154:155], v[22:25], off
	global_store_dwordx4 v[146:147], v[14:17], off offset:16
	global_store_dwordx4 v[146:147], v[6:9], off offset:512
	global_store_dwordx4 v[146:147], v[2:5], off offset:528

.LBB0_4125:
	s_ashr_i32 s49, s24, 31
	s_add_u32 s8, s8, 0x4000000
	s_addc_u32 s9, s9, 0
	s_lshl_b32 s12, s12, 5
	s_and_b32 s17, s12, 0x60
	s_mov_b64 s[12:13], 0x80
	s_add_i32 m0, s37, 0x18000
	v_lshl_add_u64 v[8:9], v[8:9], 0, s[12:13]
	s_lshl_b32 s16, s5, 13
	s_lshl_b32 s18, s17, 7
	s_waitcnt vmcnt(0)
	s_barrier
	global_load_lds_dwordx4 v[8:9], off
	v_lshl_add_u64 v[6:7], v[6:7], 0, s[12:13]
	s_add_i32 m0, s37, 0x1a000
	s_add_i32 s50, s37, 0x8000
	s_add_i32 s51, s37, 0xa000
	global_load_lds_dwordx4 v[6:7], off
	v_lshl_add_u64 v[4:5], v[4:5], 0, s[12:13]
	s_mov_b32 m0, s50
	s_add_u32 s14, s40, 0x100080
	global_load_lds_dwordx4 v[4:5], off
	v_lshl_add_u64 v[2:3], v[2:3], 0, s[12:13]
	s_mov_b32 m0, s51
	s_addc_u32 s15, s41, 0
	global_load_lds_dwordx4 v[2:3], off
	s_add_i32 m0, s37, 0x1c000
	v_lshl_add_u64 v[2:3], s[14:15], 0, v[134:135]
	global_load_lds_dwordx4 v[2:3], off
	v_lshl_add_u64 v[2:3], s[14:15], 0, v[130:131]
	s_add_i32 m0, s37, 0x1e000
	s_add_i32 s53, 0, 0x10000
	global_load_lds_dwordx4 v[2:3], off
	v_lshrrev_b32_e32 v3, 1, v10
	v_and_b32_e32 v3, 24, v3
	v_and_b32_e32 v2, 15, v10
	v_lshlrev_b32_e32 v4, 1, v3
	v_lshl_or_b32 v1, s5, 6, v2
	v_lshl_or_b32 v2, v2, 6, v4
	v_lshlrev_b32_e32 v4, 2, v10
	v_and_b32_e32 v4, 32, v4
	v_bitop3_b32 v5, v2, s16, v4 bitop3:0xde
	v_bitop3_b32 v146, v2, s18, v4 bitop3:0xde
	v_lshlrev_b32_e32 v2, 16, v11
	v_and_b32_e32 v2, 0xfffe0000, v2
	v_or_b32_e32 v147, s17, v3
	v_lshl_add_u32 v2, v12, 13, v2
	v_and_b32_e32 v3, 1, v11
	v_lshl_or_b32 v2, v3, 6, v2
	v_lshl_add_u32 v138, v13, 1, v2
	v_lshlrev_b32_e32 v2, 16, v15
	v_and_b32_e32 v2, 0xfffe0000, v2
	s_waitcnt vmcnt(6)
	v_lshl_add_u32 v2, v14, 13, v2
	v_and_b32_e32 v3, 1, v15
	v_lshl_or_b32 v2, v3, 6, v2
	s_add_i32 s54, 0, 0x14000
	s_sext_i32_i8 s59, s4
	s_mov_b32 s52, 0
	v_mov_b32_e32 v139, v135
	v_lshl_add_u32 v140, v16, 1, v2
	v_mov_b32_e32 v141, v135
	v_mov_b64_e32 v[142:143], 0x1ff
	v_add_u32_e32 v148, s53, v146
	v_add_u32_e32 v149, 0, v5
	v_add_u32_e32 v150, s54, v146
	s_mov_b32 s55, 0x100000
	s_mov_b64 s[14:15], 0x120000
	s_mov_b32 s56, 0x120000
	s_mov_b64 s[16:17], 0x140000
	s_mov_b32 s57, 0x140000
	s_mov_b64 s[18:19], 0x160000
	s_mov_b32 s58, 0x160000
	s_mov_b64 s[26:27], s[38:39]
	s_mov_b64 s[34:35], s[40:41]
	s_barrier

.LBB0_4133:
	ds_read_b128 v[152:155], v148
	ds_read_b128 v[156:159], v148 offset:1024
	ds_read_b128 v[160:163], v148 offset:2048
	ds_read_b128 v[164:167], v148 offset:3072
	ds_read_b128 v[200:203], v150
	ds_read_b128 v[204:207], v150 offset:1024
	ds_read_b128 v[208:211], v150 offset:2048
	ds_read_b128 v[212:215], v150 offset:3072
	s_add_u32 s28, s38, 0xfff00080
	s_addc_u32 s29, s39, -1
	s_cmp_eq_u32 s60, 60
	s_cselect_b32 s45, s27, s29
	s_cselect_b32 s44, s26, s28
	s_cselect_b32 s41, s35, s23
	s_cselect_b32 s40, s34, s21
	v_lshl_add_u64 v[144:145], s[38:39], 0, v[140:141]
	s_add_i32 m0, s37, 0xc000
	ds_read_b128 v[168:171], v149
	ds_read_b128 v[172:175], v149 offset:1024
	ds_read_b128 v[176:179], v149 offset:2048
	ds_read_b128 v[180:183], v149 offset:3072
	ds_read_b128 v[184:187], v149 offset:4096
	ds_read_b128 v[188:191], v149 offset:5120
	ds_read_b128 v[192:195], v149 offset:6144
	ds_read_b128 v[196:199], v149 offset:7168
	global_load_lds_dwordx4 v[144:145], off
	v_lshl_add_u64 v[144:145], s[38:39], 0, v[138:139]
	s_add_i32 m0, s37, 0xe000
	s_nop 0
	global_load_lds_dwordx4 v[144:145], off
	s_waitcnt vmcnt(8)
	s_waitcnt lgkmcnt(0)
	s_barrier
	s_setprio 1
	v_mfma_f32_16x16x32_bf16 v[126:129], v[152:155], v[168:171], v[126:129]
	v_mfma_f32_16x16x32_bf16 v[122:125], v[160:163], v[168:171], v[122:125]
	v_mfma_f32_16x16x32_bf16 v[114:117], v[152:155], v[176:179], v[114:117]
	v_mfma_f32_16x16x32_bf16 v[106:109], v[160:163], v[176:179], v[106:109]
	v_mfma_f32_16x16x32_bf16 v[98:101], v[152:155], v[184:187], v[98:101]
	v_mfma_f32_16x16x32_bf16 v[90:93], v[160:163], v[184:187], v[90:93]
	v_mfma_f32_16x16x32_bf16 v[82:85], v[152:155], v[192:195], v[82:85]
	v_mfma_f32_16x16x32_bf16 v[74:77], v[160:163], v[192:195], v[74:77]
	v_mfma_f32_16x16x32_bf16 v[126:129], v[156:159], v[172:175], v[126:129]
	v_mfma_f32_16x16x32_bf16 v[122:125], v[164:167], v[172:175], v[122:125]
	v_mfma_f32_16x16x32_bf16 v[114:117], v[156:159], v[180:183], v[114:117]
	v_mfma_f32_16x16x32_bf16 v[106:109], v[164:167], v[180:183], v[106:109]
	v_mfma_f32_16x16x32_bf16 v[98:101], v[156:159], v[188:191], v[98:101]
	v_mfma_f32_16x16x32_bf16 v[90:93], v[164:167], v[188:191], v[90:93]
	v_mfma_f32_16x16x32_bf16 v[82:85], v[156:159], v[196:199], v[82:85]
	v_mfma_f32_16x16x32_bf16 v[74:77], v[164:167], v[196:199], v[74:77]
	v_mfma_f32_16x16x32_bf16 v[118:121], v[200:203], v[168:171], v[118:121]
	v_mfma_f32_16x16x32_bf16 v[110:113], v[208:211], v[168:171], v[110:113]
	v_mfma_f32_16x16x32_bf16 v[102:105], v[200:203], v[176:179], v[102:105]
	v_mfma_f32_16x16x32_bf16 v[94:97], v[208:211], v[176:179], v[94:97]
	v_mfma_f32_16x16x32_bf16 v[86:89], v[200:203], v[184:187], v[86:89]
	v_mfma_f32_16x16x32_bf16 v[78:81], v[208:211], v[184:187], v[78:81]
	v_mfma_f32_16x16x32_bf16 v[70:73], v[200:203], v[192:195], v[70:73]
	v_mfma_f32_16x16x32_bf16 v[66:69], v[208:211], v[192:195], v[66:69]
	v_mfma_f32_16x16x32_bf16 v[118:121], v[204:207], v[172:175], v[118:121]
	v_mfma_f32_16x16x32_bf16 v[110:113], v[212:215], v[172:175], v[110:113]
	v_mfma_f32_16x16x32_bf16 v[102:105], v[204:207], v[180:183], v[102:105]
	v_mfma_f32_16x16x32_bf16 v[94:97], v[212:215], v[180:183], v[94:97]
	v_mfma_f32_16x16x32_bf16 v[86:89], v[204:207], v[188:191], v[86:89]
	v_mfma_f32_16x16x32_bf16 v[78:81], v[212:215], v[188:191], v[78:81]
	v_mfma_f32_16x16x32_bf16 v[70:73], v[204:207], v[196:199], v[70:73]
	v_mfma_f32_16x16x32_bf16 v[66:69], v[212:215], v[196:199], v[66:69]
	s_setprio 0
	s_barrier
	ds_read_b128 v[168:171], v149 offset:16384
	ds_read_b128 v[172:175], v149 offset:17408
	ds_read_b128 v[176:179], v149 offset:18432
	ds_read_b128 v[180:183], v149 offset:19456
	ds_read_b128 v[184:187], v149 offset:20480
	ds_read_b128 v[188:191], v149 offset:21504
	ds_read_b128 v[192:195], v149 offset:22528
	ds_read_b128 v[196:199], v149 offset:23552
	s_add_i32 s28, s53, s31
	v_lshl_add_u64 v[144:145], s[40:41], 0, v[134:135]
	s_mov_b32 m0, s28
	s_nop 0
	global_load_lds_dwordx4 v[144:145], off
	v_lshl_add_u64 v[216:217], s[40:41], 0, v[130:131]
	s_add_i32 m0, s28, 0x2000
	s_nop 0
	global_load_lds_dwordx4 v[216:217], off
	s_mov_b32 m0, s37
	v_lshl_add_u64 v[218:219], s[44:45], 0, v[136:137]
	global_load_lds_dwordx4 v[218:219], off
	v_lshl_add_u64 v[220:221], s[44:45], 0, v[132:133]
	s_mov_b32 m0, s46
	s_nop 0
	global_load_lds_dwordx4 v[220:221], off
	s_add_u32 s28, s40, 0x100000
	s_addc_u32 s29, s41, 0
	s_add_i32 s61, s54, s31
	v_lshl_add_u64 v[226:227], s[28:29], 0, v[134:135]
	s_mov_b32 m0, s61
	s_nop 0
	global_load_lds_dwordx4 v[226:227], off
	v_lshl_add_u64 v[226:227], s[28:29], 0, v[130:131]
	s_add_i32 m0, s61, 0x2000
	s_nop 0
	global_load_lds_dwordx4 v[226:227], off
	s_waitcnt vmcnt(8)
	s_waitcnt lgkmcnt(0)
	s_barrier
	s_setprio 1
	v_mfma_f32_16x16x32_bf16 v[62:65], v[152:155], v[168:171], v[62:65]
	v_mfma_f32_16x16x32_bf16 v[58:61], v[160:163], v[168:171], v[58:61]
	v_mfma_f32_16x16x32_bf16 v[54:57], v[152:155], v[176:179], v[54:57]
	v_mfma_f32_16x16x32_bf16 v[46:49], v[160:163], v[176:179], v[46:49]
	v_mfma_f32_16x16x32_bf16 v[38:41], v[152:155], v[184:187], v[38:41]
	v_mfma_f32_16x16x32_bf16 v[30:33], v[160:163], v[184:187], v[30:33]
	v_mfma_f32_16x16x32_bf16 v[22:25], v[152:155], v[192:195], v[22:25]
	v_mfma_f32_16x16x32_bf16 v[14:17], v[160:163], v[192:195], v[14:17]
	v_mfma_f32_16x16x32_bf16 v[62:65], v[156:159], v[172:175], v[62:65]
	v_mfma_f32_16x16x32_bf16 v[58:61], v[164:167], v[172:175], v[58:61]
	v_mfma_f32_16x16x32_bf16 v[54:57], v[156:159], v[180:183], v[54:57]
	v_mfma_f32_16x16x32_bf16 v[46:49], v[164:167], v[180:183], v[46:49]
	v_mfma_f32_16x16x32_bf16 v[38:41], v[156:159], v[188:191], v[38:41]
	v_mfma_f32_16x16x32_bf16 v[30:33], v[164:167], v[188:191], v[30:33]
	v_mfma_f32_16x16x32_bf16 v[22:25], v[156:159], v[196:199], v[22:25]
	v_mfma_f32_16x16x32_bf16 v[14:17], v[164:167], v[196:199], v[14:17]
	v_mfma_f32_16x16x32_bf16 v[50:53], v[200:203], v[168:171], v[50:53]
	v_mfma_f32_16x16x32_bf16 v[42:45], v[208:211], v[168:171], v[42:45]
	v_mfma_f32_16x16x32_bf16 v[34:37], v[200:203], v[176:179], v[34:37]
	v_mfma_f32_16x16x32_bf16 v[26:29], v[208:211], v[176:179], v[26:29]
	v_mfma_f32_16x16x32_bf16 v[18:21], v[200:203], v[184:187], v[18:21]
	v_mfma_f32_16x16x32_bf16 v[10:13], v[208:211], v[184:187], v[10:13]
	v_mfma_f32_16x16x32_bf16 v[6:9], v[200:203], v[192:195], v[6:9]
	v_mfma_f32_16x16x32_bf16 v[2:5], v[208:211], v[192:195], v[2:5]
	v_mfma_f32_16x16x32_bf16 v[50:53], v[204:207], v[172:175], v[50:53]
	v_mfma_f32_16x16x32_bf16 v[42:45], v[212:215], v[172:175], v[42:45]
	v_mfma_f32_16x16x32_bf16 v[34:37], v[204:207], v[180:183], v[34:37]
	v_mfma_f32_16x16x32_bf16 v[26:29], v[212:215], v[180:183], v[26:29]
	v_mfma_f32_16x16x32_bf16 v[18:21], v[204:207], v[188:191], v[18:21]
	v_mfma_f32_16x16x32_bf16 v[10:13], v[212:215], v[188:191], v[10:13]
	v_mfma_f32_16x16x32_bf16 v[6:9], v[204:207], v[196:199], v[6:9]
	v_mfma_f32_16x16x32_bf16 v[2:5], v[212:215], v[196:199], v[2:5]
	s_setprio 0
	s_add_i32 s61, 0, 0x18000
	v_add_u32_e32 v151, s61, v146
	s_barrier
	ds_read_b128 v[152:155], v151
	ds_read_b128 v[156:159], v151 offset:1024
	ds_read_b128 v[160:163], v151 offset:2048
	ds_read_b128 v[164:167], v151 offset:3072
	ds_read_b128 v[200:203], v151 offset:16384
	ds_read_b128 v[204:207], v151 offset:17408
	ds_read_b128 v[208:211], v151 offset:18432
	ds_read_b128 v[212:215], v151 offset:19456
	s_add_u32 s28, s44, 0x100000
	s_addc_u32 s29, s45, 0
	s_mov_b32 m0, s47
	v_lshl_add_u64 v[226:227], s[28:29], 0, v[136:137]
	ds_read_b128 v[168:171], v149 offset:32768
	ds_read_b128 v[172:175], v149 offset:33792
	ds_read_b128 v[176:179], v149 offset:34816
	ds_read_b128 v[180:183], v149 offset:35840
	ds_read_b128 v[184:187], v149 offset:36864
	ds_read_b128 v[188:191], v149 offset:37888
	ds_read_b128 v[192:195], v149 offset:38912
	ds_read_b128 v[196:199], v149 offset:39936
	global_load_lds_dwordx4 v[226:227], off
	v_lshl_add_u64 v[226:227], s[28:29], 0, v[132:133]
	s_mov_b32 m0, s48
	s_nop 0
	global_load_lds_dwordx4 v[226:227], off
	s_waitcnt vmcnt(8)
	s_waitcnt lgkmcnt(0)
	s_barrier
	s_setprio 1
	v_mfma_f32_16x16x32_bf16 v[126:129], v[152:155], v[168:171], v[126:129]
	v_mfma_f32_16x16x32_bf16 v[122:125], v[160:163], v[168:171], v[122:125]
	v_mfma_f32_16x16x32_bf16 v[114:117], v[152:155], v[176:179], v[114:117]
	v_mfma_f32_16x16x32_bf16 v[106:109], v[160:163], v[176:179], v[106:109]
	v_mfma_f32_16x16x32_bf16 v[98:101], v[152:155], v[184:187], v[98:101]
	v_mfma_f32_16x16x32_bf16 v[90:93], v[160:163], v[184:187], v[90:93]
	v_mfma_f32_16x16x32_bf16 v[82:85], v[152:155], v[192:195], v[82:85]
	v_mfma_f32_16x16x32_bf16 v[74:77], v[160:163], v[192:195], v[74:77]
	v_mfma_f32_16x16x32_bf16 v[126:129], v[156:159], v[172:175], v[126:129]
	v_mfma_f32_16x16x32_bf16 v[122:125], v[164:167], v[172:175], v[122:125]
	v_mfma_f32_16x16x32_bf16 v[114:117], v[156:159], v[180:183], v[114:117]
	v_mfma_f32_16x16x32_bf16 v[106:109], v[164:167], v[180:183], v[106:109]
	v_mfma_f32_16x16x32_bf16 v[98:101], v[156:159], v[188:191], v[98:101]
	v_mfma_f32_16x16x32_bf16 v[90:93], v[164:167], v[188:191], v[90:93]
	v_mfma_f32_16x16x32_bf16 v[82:85], v[156:159], v[196:199], v[82:85]
	v_mfma_f32_16x16x32_bf16 v[74:77], v[164:167], v[196:199], v[74:77]
	v_mfma_f32_16x16x32_bf16 v[118:121], v[200:203], v[168:171], v[118:121]
	v_mfma_f32_16x16x32_bf16 v[110:113], v[208:211], v[168:171], v[110:113]
	v_mfma_f32_16x16x32_bf16 v[102:105], v[200:203], v[176:179], v[102:105]
	v_mfma_f32_16x16x32_bf16 v[94:97], v[208:211], v[176:179], v[94:97]
	v_mfma_f32_16x16x32_bf16 v[86:89], v[200:203], v[184:187], v[86:89]
	v_mfma_f32_16x16x32_bf16 v[78:81], v[208:211], v[184:187], v[78:81]
	v_mfma_f32_16x16x32_bf16 v[70:73], v[200:203], v[192:195], v[70:73]
	v_mfma_f32_16x16x32_bf16 v[66:69], v[208:211], v[192:195], v[66:69]
	v_mfma_f32_16x16x32_bf16 v[118:121], v[204:207], v[172:175], v[118:121]
	v_mfma_f32_16x16x32_bf16 v[110:113], v[212:215], v[172:175], v[110:113]
	v_mfma_f32_16x16x32_bf16 v[102:105], v[204:207], v[180:183], v[102:105]
	v_mfma_f32_16x16x32_bf16 v[94:97], v[212:215], v[180:183], v[94:97]
	v_mfma_f32_16x16x32_bf16 v[86:89], v[204:207], v[188:191], v[86:89]
	v_mfma_f32_16x16x32_bf16 v[78:81], v[212:215], v[188:191], v[78:81]
	v_mfma_f32_16x16x32_bf16 v[70:73], v[204:207], v[196:199], v[70:73]
	v_mfma_f32_16x16x32_bf16 v[66:69], v[212:215], v[196:199], v[66:69]
	s_setprio 0
	s_barrier
	ds_read_b128 v[168:171], v149 offset:49152
	ds_read_b128 v[172:175], v149 offset:50176
	ds_read_b128 v[176:179], v149 offset:51200
	ds_read_b128 v[180:183], v149 offset:52224
	ds_read_b128 v[184:187], v149 offset:53248
	ds_read_b128 v[188:191], v149 offset:54272
	ds_read_b128 v[192:195], v149 offset:55296
	ds_read_b128 v[196:199], v149 offset:56320
	s_add_i32 s44, 0, 0x1c000
	s_add_i32 s28, s61, s31
	v_lshl_add_u64 v[144:145], v[144:145], 0, s[12:13]
	s_mov_b32 m0, s28
	s_nop 0
	global_load_lds_dwordx4 v[144:145], off
	v_lshl_add_u64 v[144:145], v[216:217], 0, s[12:13]
	s_add_i32 m0, s28, 0x2000
	s_nop 0
	global_load_lds_dwordx4 v[144:145], off
	s_mov_b32 m0, s50
	v_lshl_add_u64 v[144:145], v[218:219], 0, s[12:13]
	global_load_lds_dwordx4 v[144:145], off
	v_lshl_add_u64 v[144:145], v[220:221], 0, s[12:13]
	s_mov_b32 m0, s51
	s_nop 0
	global_load_lds_dwordx4 v[144:145], off
	s_add_u32 s28, s40, 0x100080
	s_addc_u32 s29, s41, 0
	s_add_i32 s40, s44, s31
	v_lshl_add_u64 v[144:145], s[28:29], 0, v[134:135]
	s_mov_b32 m0, s40
	s_nop 0
	global_load_lds_dwordx4 v[144:145], off
	v_lshl_add_u64 v[144:145], s[28:29], 0, v[130:131]
	s_add_i32 m0, s40, 0x2000
	s_nop 0
	global_load_lds_dwordx4 v[144:145], off
	s_waitcnt vmcnt(8)
	s_waitcnt lgkmcnt(0)
	s_barrier
	s_setprio 1
	v_mfma_f32_16x16x32_bf16 v[62:65], v[152:155], v[168:171], v[62:65]
	v_mfma_f32_16x16x32_bf16 v[58:61], v[160:163], v[168:171], v[58:61]
	v_mfma_f32_16x16x32_bf16 v[54:57], v[152:155], v[176:179], v[54:57]
	v_mfma_f32_16x16x32_bf16 v[46:49], v[160:163], v[176:179], v[46:49]
	v_mfma_f32_16x16x32_bf16 v[38:41], v[152:155], v[184:187], v[38:41]
	v_mfma_f32_16x16x32_bf16 v[30:33], v[160:163], v[184:187], v[30:33]
	v_mfma_f32_16x16x32_bf16 v[22:25], v[152:155], v[192:195], v[22:25]
	v_mfma_f32_16x16x32_bf16 v[14:17], v[160:163], v[192:195], v[14:17]
	v_mfma_f32_16x16x32_bf16 v[62:65], v[156:159], v[172:175], v[62:65]
	v_mfma_f32_16x16x32_bf16 v[58:61], v[164:167], v[172:175], v[58:61]
	v_mfma_f32_16x16x32_bf16 v[54:57], v[156:159], v[180:183], v[54:57]
	v_mfma_f32_16x16x32_bf16 v[46:49], v[164:167], v[180:183], v[46:49]
	v_mfma_f32_16x16x32_bf16 v[38:41], v[156:159], v[188:191], v[38:41]
	v_mfma_f32_16x16x32_bf16 v[30:33], v[164:167], v[188:191], v[30:33]
	v_mfma_f32_16x16x32_bf16 v[22:25], v[156:159], v[196:199], v[22:25]
	v_mfma_f32_16x16x32_bf16 v[14:17], v[164:167], v[196:199], v[14:17]
	v_mfma_f32_16x16x32_bf16 v[50:53], v[200:203], v[168:171], v[50:53]
	v_mfma_f32_16x16x32_bf16 v[42:45], v[208:211], v[168:171], v[42:45]
	v_mfma_f32_16x16x32_bf16 v[34:37], v[200:203], v[176:179], v[34:37]
	v_mfma_f32_16x16x32_bf16 v[26:29], v[208:211], v[176:179], v[26:29]
	v_mfma_f32_16x16x32_bf16 v[18:21], v[200:203], v[184:187], v[18:21]
	v_mfma_f32_16x16x32_bf16 v[10:13], v[208:211], v[184:187], v[10:13]
	v_mfma_f32_16x16x32_bf16 v[6:9], v[200:203], v[192:195], v[6:9]
	v_mfma_f32_16x16x32_bf16 v[2:5], v[208:211], v[192:195], v[2:5]
	v_mfma_f32_16x16x32_bf16 v[50:53], v[204:207], v[172:175], v[50:53]
	v_mfma_f32_16x16x32_bf16 v[42:45], v[212:215], v[172:175], v[42:45]
	v_mfma_f32_16x16x32_bf16 v[34:37], v[204:207], v[180:183], v[34:37]
	v_mfma_f32_16x16x32_bf16 v[26:29], v[212:215], v[180:183], v[26:29]
	v_mfma_f32_16x16x32_bf16 v[18:21], v[204:207], v[188:191], v[18:21]
	v_mfma_f32_16x16x32_bf16 v[10:13], v[212:215], v[188:191], v[10:13]
	v_mfma_f32_16x16x32_bf16 v[6:9], v[204:207], v[196:199], v[6:9]
	v_mfma_f32_16x16x32_bf16 v[2:5], v[212:215], v[196:199], v[2:5]
	s_setprio 0
	s_add_i32 s60, s60, 2
	s_add_u32 s21, s21, 0x100
	s_addc_u32 s23, s23, 0
	s_add_u32 s38, s38, 0x100
	s_addc_u32 s39, s39, 0
	s_cmp_gt_u32 s60, 61
	s_barrier
	s_cbranch_scc0 .LBB0_4133
	v_lshl_add_u32 v152, s36, 8, v1
	v_lshl_or_b32 v144, s59, 8, v147
	v_ashrrev_i32_e32 v153, 31, v152
	v_ashrrev_i32_e32 v145, 31, v144
	v_lshlrev_b64 v[154:155], 13, v[152:153]
	v_lshl_add_u64 v[154:155], s[8:9], 0, v[154:155]
	v_lshlrev_b64 v[156:157], 1, v[144:145]
	v_lshl_add_u64 v[144:145], v[154:155], 0, v[156:157]
	v_cvt_pk_bf16_f32 v126, v126, v127
	v_cvt_pk_bf16_f32 v127, v128, v129
	v_cvt_pk_bf16_f32 v128, v122, v123
	v_cvt_pk_bf16_f32 v129, v124, v125
	global_store_dwordx4 v[144:145], v[126:129], off
	v_cvt_pk_bf16_f32 v118, v118, v119
	v_cvt_pk_bf16_f32 v119, v120, v121
	v_cvt_pk_bf16_f32 v120, v110, v111
	v_or_b32_e32 v110, 16, v152
	v_ashrrev_i32_e32 v111, 31, v110
	v_lshlrev_b64 v[110:111], 13, v[110:111]
	v_lshl_add_u64 v[110:111], s[8:9], 0, v[110:111]
	v_cvt_pk_bf16_f32 v121, v112, v113
	global_store_dwordx4 v[144:145], v[118:121], off offset:256
	s_mov_b32 s36, s22
	s_mov_b32 s59, s20
	v_lshl_add_u64 v[118:119], v[110:111], 0, v[156:157]
	v_cvt_pk_bf16_f32 v110, v114, v115
	v_cvt_pk_bf16_f32 v111, v116, v117
	v_cvt_pk_bf16_f32 v112, v106, v107
	v_cvt_pk_bf16_f32 v113, v108, v109
	global_store_dwordx4 v[118:119], v[110:113], off
	v_cvt_pk_bf16_f32 v102, v102, v103
	v_cvt_pk_bf16_f32 v103, v104, v105
	v_cvt_pk_bf16_f32 v104, v94, v95
	v_or_b32_e32 v94, 32, v152
	v_ashrrev_i32_e32 v95, 31, v94
	v_lshlrev_b64 v[94:95], 13, v[94:95]
	v_lshl_add_u64 v[94:95], s[8:9], 0, v[94:95]
	v_cvt_pk_bf16_f32 v105, v96, v97
	global_store_dwordx4 v[118:119], v[102:105], off offset:256
	s_mov_b64 s[40:41], s[34:35]
	s_mov_b64 s[38:39], s[26:27]
	v_lshl_add_u64 v[102:103], v[94:95], 0, v[156:157]
	v_cvt_pk_bf16_f32 v94, v98, v99
	v_cvt_pk_bf16_f32 v95, v100, v101
	v_cvt_pk_bf16_f32 v96, v90, v91
	v_cvt_pk_bf16_f32 v97, v92, v93
	global_store_dwordx4 v[102:103], v[94:97], off
	v_cvt_pk_bf16_f32 v86, v86, v87
	v_cvt_pk_bf16_f32 v87, v88, v89
	v_cvt_pk_bf16_f32 v88, v78, v79
	v_or_b32_e32 v78, 48, v152
	v_ashrrev_i32_e32 v79, 31, v78
	v_lshlrev_b64 v[78:79], 13, v[78:79]
	v_lshl_add_u64 v[78:79], s[8:9], 0, v[78:79]
	v_cvt_pk_bf16_f32 v89, v80, v81
	global_store_dwordx4 v[102:103], v[86:89], off offset:256
	s_nop 1
	v_lshl_add_u64 v[86:87], v[78:79], 0, v[156:157]
	v_cvt_pk_bf16_f32 v78, v82, v83
	v_cvt_pk_bf16_f32 v79, v84, v85
	v_cvt_pk_bf16_f32 v80, v74, v75
	v_cvt_pk_bf16_f32 v81, v76, v77
	global_store_dwordx4 v[86:87], v[78:81], off
	v_cvt_pk_bf16_f32 v70, v70, v71
	v_cvt_pk_bf16_f32 v71, v72, v73
	v_cvt_pk_bf16_f32 v72, v66, v67
	v_cvt_pk_bf16_f32 v73, v68, v69
	global_store_dwordx4 v[86:87], v[70:73], off offset:256
	v_cvt_pk_bf16_f32 v62, v62, v63
	v_cvt_pk_bf16_f32 v63, v64, v65
	v_cvt_pk_bf16_f32 v64, v58, v59
	v_add_co_u32_e32 v58, vcc, s55, v144
	v_lshl_add_u64 v[66:67], v[144:145], 0, s[6:7]
	s_nop 0
	v_addc_co_u32_e32 v59, vcc, 0, v145, vcc
	v_cvt_pk_bf16_f32 v65, v60, v61
	global_store_dwordx4 v[58:59], v[62:65], off
	v_cvt_pk_bf16_f32 v50, v50, v51
	v_cvt_pk_bf16_f32 v51, v52, v53
	v_cvt_pk_bf16_f32 v52, v42, v43
	v_cvt_pk_bf16_f32 v53, v44, v45
	global_store_dwordx4 v[66:67], v[50:53], off offset:256
	v_cvt_pk_bf16_f32 v42, v54, v55
	v_cvt_pk_bf16_f32 v43, v56, v57
	v_cvt_pk_bf16_f32 v44, v46, v47
	v_add_co_u32_e32 v46, vcc, s56, v144
	s_nop 0
	v_lshl_add_u64 v[50:51], v[144:145], 0, s[14:15]
	v_addc_co_u32_e32 v47, vcc, 0, v145, vcc
	v_cvt_pk_bf16_f32 v45, v48, v49
	global_store_dwordx4 v[46:47], v[42:45], off
	v_cvt_pk_bf16_f32 v34, v34, v35
	v_cvt_pk_bf16_f32 v35, v36, v37
	v_cvt_pk_bf16_f32 v36, v26, v27
	v_cvt_pk_bf16_f32 v37, v28, v29
	global_store_dwordx4 v[50:51], v[34:37], off offset:256
	v_cvt_pk_bf16_f32 v26, v38, v39
	v_cvt_pk_bf16_f32 v27, v40, v41
	v_cvt_pk_bf16_f32 v28, v30, v31
	v_add_co_u32_e32 v30, vcc, s57, v144
	s_nop 0
	v_lshl_add_u64 v[34:35], v[144:145], 0, s[16:17]
	v_addc_co_u32_e32 v31, vcc, 0, v145, vcc
	v_cvt_pk_bf16_f32 v29, v32, v33
	global_store_dwordx4 v[30:31], v[26:29], off
	v_cvt_pk_bf16_f32 v18, v18, v19
	v_cvt_pk_bf16_f32 v19, v20, v21
	v_cvt_pk_bf16_f32 v20, v10, v11
	v_cvt_pk_bf16_f32 v21, v12, v13
	global_store_dwordx4 v[34:35], v[18:21], off offset:256
	v_cvt_pk_bf16_f32 v10, v22, v23
	v_cvt_pk_bf16_f32 v11, v24, v25
	v_cvt_pk_bf16_f32 v12, v14, v15
	v_add_co_u32_e32 v14, vcc, s58, v144
	s_nop 0
	v_lshl_add_u64 v[18:19], v[144:145], 0, s[18:19]
	v_addc_co_u32_e32 v15, vcc, 0, v145, vcc
	s_and_b64 vcc, exec, s[4:5]
	v_cvt_pk_bf16_f32 v13, v16, v17
	global_store_dwordx4 v[14:15], v[10:13], off
	v_cvt_pk_bf16_f32 v6, v6, v7
	v_cvt_pk_bf16_f32 v7, v8, v9
	v_cvt_pk_bf16_f32 v8, v2, v3
	v_cvt_pk_bf16_f32 v9, v4, v5
	global_store_dwordx4 v[18:19], v[6:9], off offset:256
	s_cbranch_vccz .LBB0_4126
	s_waitcnt vmcnt(0)
	s_cmpk_gt_u32 s11, 0xff
	s_cbranch_scc1 .LBB0_4137
	s_barrier
